# P8 cross-attention: K and V^T staging de-serialised (16 loads per thread up front, counted waits per LDS write) on top of v6
# baseline (speedup 1.0000x reference)
; #define LAS __attribute__((address_space(3)))
; #define MFMA16(a, b, c) __builtin_amdgcn_mfma_f32_16x16x32_bf16((a), (b), (c), 0, 0, 0)
; __device__ __forceinline__ void xattn_pair(LAS unsigned char* lds, int bh, size_t row_base, bf16* QO, const bf16* Kx, const bf16* VTx, int tid, const WsRef& wsr) {
;     ...
; #pragma unroll 4
;     for (int i = 0; i < 16; ++i) { const int id = tid + 512 * i, r = id >> 5, ch = id & 31; *(LAS u32x4*)(T + r * LDX + ch * 8) = kg[id]; }
;     __syncthreads();
;     bf16x8 pf0[8], pf1[8]; float rinv0, rinv1;
; #pragma unroll
;     for (int half = 0; half < 2; ++half) {
;         const bf16* qp = half ? qp1 : qp0;
;         bf16x8 qf[8];
; #pragma unroll
;         for (int kk = 0; kk < 8; ++kk) qf[kk] = *(const bf16x8*)(qp + kk * 32 + fq * 8);
;         f32x4 sx[16];
; #pragma unroll
;         for (int n = 0; n < 16; ++n) sx[n] = (f32x4){0.f, 0.f, 0.f, 0.f};
; #pragma unroll
;         for (int kk = 0; kk < 8; ++kk)
; #pragma unroll
;             for (int n = 0; n < 16; ++n) { const bf16x8 kf = *(const LAS bf16x8*)(T + (n * 16 + fr) * LDX + kk * 32 + fq * 8); sx[n] = MFMA16(kf, qf[kk], sx[n]); }
.LBB0_704:
	s_mov_b32 s9, 0
	s_mov_b32 s8, 0x2200000
	v_lshl_add_u64 v[16:17], v[84:85], 0, s[8:9]
	global_load_dwordx4 v[20:23], v[16:17], off
	s_mov_b32 s8, 0x2202000
	v_lshl_add_u64 v[16:17], v[84:85], 0, s[8:9]
	global_load_dwordx4 v[24:27], v[16:17], off
	s_mov_b32 s8, 0x2204000
	v_lshl_add_u64 v[16:17], v[84:85], 0, s[8:9]
	global_load_dwordx4 v[28:31], v[16:17], off
	s_mov_b32 s8, 0x2206000
	v_lshl_add_u64 v[16:17], v[84:85], 0, s[8:9]
	global_load_dwordx4 v[32:35], v[16:17], off
	s_mov_b32 s8, 0x2208000
	v_lshl_add_u64 v[16:17], v[84:85], 0, s[8:9]
	global_load_dwordx4 v[36:39], v[16:17], off
	s_mov_b32 s8, 0x220a000
	v_lshl_add_u64 v[16:17], v[84:85], 0, s[8:9]
	global_load_dwordx4 v[40:43], v[16:17], off
	s_mov_b32 s8, 0x220c000
	v_lshl_add_u64 v[16:17], v[84:85], 0, s[8:9]
	global_load_dwordx4 v[44:47], v[16:17], off
	s_mov_b32 s8, 0x220e000
	v_lshl_add_u64 v[16:17], v[84:85], 0, s[8:9]
	global_load_dwordx4 v[48:51], v[16:17], off
	s_mov_b32 s8, 0x2210000
	v_lshl_add_u64 v[16:17], v[84:85], 0, s[8:9]
	global_load_dwordx4 v[52:55], v[16:17], off
	s_mov_b32 s8, 0x2212000
	v_lshl_add_u64 v[16:17], v[84:85], 0, s[8:9]
	global_load_dwordx4 v[56:59], v[16:17], off
	s_mov_b32 s8, 0x2214000
	v_lshl_add_u64 v[16:17], v[84:85], 0, s[8:9]
	global_load_dwordx4 v[60:63], v[16:17], off
	s_mov_b32 s8, 0x2216000
	v_lshl_add_u64 v[16:17], v[84:85], 0, s[8:9]
	global_load_dwordx4 v[64:67], v[16:17], off
	s_mov_b32 s8, 0x2218000
	v_lshl_add_u64 v[16:17], v[84:85], 0, s[8:9]
	global_load_dwordx4 v[68:71], v[16:17], off
	s_mov_b32 s8, 0x221a000
	v_lshl_add_u64 v[16:17], v[84:85], 0, s[8:9]
	global_load_dwordx4 v[72:75], v[16:17], off
	s_mov_b32 s8, 0x221c000
	v_lshl_add_u64 v[16:17], v[84:85], 0, s[8:9]
	global_load_dwordx4 v[76:79], v[16:17], off
	s_mov_b32 s8, 0x221e000
	v_lshl_add_u64 v[16:17], v[84:85], 0, s[8:9]
	global_load_dwordx4 v[80:83], v[16:17], off
	v_add_u32_e32 v12, 0x10800, v1
	v_add_u32_e32 v13, 0x10800, v2
	v_add_u32_e32 v14, 0x10800, v0
	v_add_u32_e32 v15, 0x10800, v3
	s_waitcnt vmcnt(15)
	ds_write_b128 v1, v[20:23]
	s_waitcnt vmcnt(14)
	ds_write_b128 v2, v[24:27]
	s_waitcnt vmcnt(13)
	ds_write_b128 v0, v[28:31]
	s_waitcnt vmcnt(12)
	ds_write_b128 v3, v[32:35]
	s_waitcnt vmcnt(11)
	ds_write_b128 v1, v[36:39] offset:33792
	s_waitcnt vmcnt(10)
	ds_write_b128 v2, v[40:43] offset:33792
	s_waitcnt vmcnt(9)
	ds_write_b128 v0, v[44:47] offset:33792
	s_waitcnt vmcnt(8)
	ds_write_b128 v3, v[48:51] offset:33792
	s_waitcnt vmcnt(7)
	ds_write_b128 v12, v[52:55]
	s_waitcnt vmcnt(6)
	ds_write_b128 v13, v[56:59]
	s_waitcnt vmcnt(5)
	ds_write_b128 v14, v[60:63]
	s_waitcnt vmcnt(4)
	ds_write_b128 v15, v[64:67]
	s_waitcnt vmcnt(3)
	ds_write_b128 v12, v[68:71] offset:33792
	s_waitcnt vmcnt(2)
	ds_write_b128 v13, v[72:75] offset:33792
	s_waitcnt vmcnt(1)
	ds_write_b128 v14, v[76:79] offset:33792
	s_waitcnt vmcnt(0)
	ds_write_b128 v15, v[80:83] offset:33792
	s_ashr_i32 s13, s12, 31
	v_lshrrev_b32_e32 v0, 2, v128
	s_lshl_b64 s[8:9], s[12:13], 8
	v_and_b32_e32 v100, 15, v128
	v_and_b32_e32 v0, 0xf0, v0
	v_or3_b32 v0, s8, v100, v0
	v_mov_b32_e32 v1, s9
	v_lshlrev_b64 v[0:1], 11, v[0:1]
	s_lshl_b32 s8, s33, 9
	v_lshl_add_u64 v[0:1], s[70:71], 0, v[0:1]
	s_and_b32 s8, s8, 0x600
	s_mov_b32 s9, 0
	v_lshl_add_u64 v[96:97], v[0:1], 0, s[8:9]
	v_bfe_u32 v0, v128, 4, 2
	v_lshlrev_b32_e32 v86, 4, v0
	v_mov_b32_e32 v87, 0
	v_lshl_add_u64 v[28:29], v[96:97], 0, v[86:87]
	s_waitcnt lgkmcnt(0)
	s_barrier
	v_lshlrev_b32_e32 v109, 3, v0
	global_load_dwordx4 v[36:39], v[28:29], off
	global_load_dwordx4 v[24:27], v[28:29], off offset:64
	global_load_dwordx4 v[20:23], v[28:29], off offset:128
	global_load_dwordx4 v[16:19], v[28:29], off offset:192
	global_load_dwordx4 v[12:15], v[28:29], off offset:256
	global_load_dwordx4 v[8:11], v[28:29], off offset:320
	global_load_dwordx4 v[4:7], v[28:29], off offset:384
	global_load_dwordx4 v[0:3], v[28:29], off offset:448
	s_mov_b64 s[8:9], 0x40000
	v_lshl_add_u64 v[98:99], v[96:97], 0, s[8:9]
	v_add_u32_e32 v95, 0, v86
	s_movk_i32 s8, 0x210
	v_mad_u32_u24 v94, v100, s8, v95
	ds_read_b128 v[28:31], v94
	v_mov_b32_e32 v101, 0x1ef00
	v_mad_u32_u24 v101, v100, s8, v101
	v_add_u32_e32 v163, v95, v101
	ds_read_b128 v[118:121], v163
	v_mov_b32_e32 v32, 0x12900
	v_mov_b32_e32 v40, 0x14a00
	v_mad_u32_u24 v103, v100, s8, v32
	v_mad_u32_u24 v106, v100, s8, v40
	v_add_u32_e32 v157, v95, v103
	v_add_u32_e32 v158, v95, v106
	v_mul_u32_u24_e32 v88, 0x210, v100
	v_or_b32_e32 v93, 0x400, v128
	s_waitcnt vmcnt(7) lgkmcnt(1)
	v_mfma_f32_16x16x32_bf16 v[110:113], v[28:31], v[36:39], 0
	ds_read_b128 v[28:31], v94 offset:8448
	ds_read_b128 v[32:35], v157
	ds_read_b128 v[40:43], v158
	s_waitcnt lgkmcnt(2)
	v_mfma_f32_16x16x32_bf16 v[114:117], v[28:31], v[36:39], 0
	ds_read_b128 v[28:31], v94 offset:16896
	s_waitcnt lgkmcnt(0)
	v_mfma_f32_16x16x32_bf16 v[80:83], v[28:31], v[36:39], 0
	ds_read_b128 v[28:31], v94 offset:25344
	s_waitcnt lgkmcnt(0)
	v_mfma_f32_16x16x32_bf16 v[76:79], v[28:31], v[36:39], 0
	ds_read_b128 v[28:31], v94 offset:33792
	s_waitcnt lgkmcnt(0)
	v_mfma_f32_16x16x32_bf16 v[72:75], v[28:31], v[36:39], 0
	ds_read_b128 v[28:31], v94 offset:42240
	v_mfma_f32_16x16x32_bf16 v[44:47], v[40:43], v[36:39], 0
	v_mov_b32_e32 v40, 0x16b00
	v_mad_u32_u24 v108, v100, s8, v40
	v_add_u32_e32 v159, v95, v108
	s_waitcnt lgkmcnt(0)
	v_mfma_f32_16x16x32_bf16 v[68:71], v[28:31], v[36:39], 0
	ds_read_b128 v[28:31], v94 offset:50688
	ds_read_b128 v[40:43], v159
	s_waitcnt lgkmcnt(0)
	v_mfma_f32_16x16x32_bf16 v[56:59], v[40:43], v[36:39], 0
	v_mov_b32_e32 v40, 0x18c00
	v_mad_u32_u24 v107, v100, s8, v40
	v_add_u32_e32 v160, v95, v107
	v_mfma_f32_16x16x32_bf16 v[64:67], v[28:31], v[36:39], 0
	ds_read_b128 v[28:31], v94 offset:59136
	ds_read_b128 v[40:43], v160
	s_waitcnt lgkmcnt(1)
; #define LAS __attribute__((address_space(3)))
; #define MFMA16(a, b, c) __builtin_amdgcn_mfma_f32_16x16x32_bf16((a), (b), (c), 0, 0, 0)
; __device__ __forceinline__ void xattn_pair(LAS unsigned char* lds, int bh, size_t row_base, bf16* QO, const bf16* Kx, const bf16* VTx, int tid, const WsRef& wsr) {
;     ...
; #pragma unroll
;         for (int kk = 0; kk < 8; ++kk)
; #pragma unroll
;             for (int n = 0; n < 16; ++n) { const bf16x8 kf = *(const LAS bf16x8*)(T + (n * 16 + fr) * LDX + kk * 32 + fq * 8); sx[n] = MFMA16(kf, qf[kk], sx[n]); }
	v_mfma_f32_16x16x32_bf16 v[60:63], v[28:31], v[36:39], 0
	v_mov_b32_e32 v28, 0x10800
	v_mad_u32_u24 v97, v100, s8, v28
	v_add_u32_e32 v156, v95, v97
	s_waitcnt lgkmcnt(0)
	v_mfma_f32_16x16x32_bf16 v[52:55], v[40:43], v[36:39], 0
	v_mov_b32_e32 v40, 0x1ad00
	v_mad_u32_u24 v105, v100, s8, v40
	v_add_u32_e32 v161, v95, v105
	ds_read_b128 v[28:31], v156
	ds_read_b128 v[40:43], v161
	s_waitcnt lgkmcnt(0)
	v_mfma_f32_16x16x32_bf16 v[48:51], v[40:43], v[36:39], 0
	v_mov_b32_e32 v40, 0x1ce00
	v_mad_u32_u24 v104, v100, s8, v40
	v_add_u32_e32 v162, v95, v104
	ds_read_b128 v[40:43], v162
	v_mfma_f32_16x16x32_bf16 v[28:31], v[28:31], v[36:39], 0
	v_add_u32_e32 v100, 64, v95
	v_add_u32_e32 v164, v100, v97
	v_add_u32_e32 v165, v100, v103
	v_mfma_f32_16x16x32_bf16 v[32:35], v[32:35], v[36:39], 0
	v_add_u32_e32 v166, v100, v106
	v_add_u32_e32 v167, v100, v108
	v_add_u32_e32 v168, v100, v107
	s_waitcnt lgkmcnt(0)
	v_mfma_f32_16x16x32_bf16 v[40:43], v[40:43], v[36:39], 0
	v_add_u32_e32 v169, v100, v105
	v_add_u32_e32 v170, v100, v104
	v_add_u32_e32 v171, v100, v101
	v_mfma_f32_16x16x32_bf16 v[36:39], v[118:121], v[36:39], 0
	ds_read_b128 v[118:121], v94 offset:64
	v_add_u32_e32 v100, 0x80, v95
	v_add_u32_e32 v172, v100, v97
	s_waitcnt vmcnt(6) lgkmcnt(0)
	v_mfma_f32_16x16x32_bf16 v[110:113], v[118:121], v[24:27], v[110:113]
	ds_read_b128 v[118:121], v94 offset:8512
	v_add_u32_e32 v173, v100, v103
	v_add_u32_e32 v174, v100, v106
	s_waitcnt lgkmcnt(0)
	v_mfma_f32_16x16x32_bf16 v[114:117], v[118:121], v[24:27], v[114:117]
	ds_read_b128 v[118:121], v94 offset:16960
	v_add_u32_e32 v175, v100, v108
	v_add_u32_e32 v176, v100, v107
	s_waitcnt lgkmcnt(0)
	v_mfma_f32_16x16x32_bf16 v[80:83], v[118:121], v[24:27], v[80:83]
	ds_read_b128 v[118:121], v94 offset:25408
	v_add_u32_e32 v177, v100, v105
	v_add_u32_e32 v178, v100, v104
	s_waitcnt lgkmcnt(0)
	v_mfma_f32_16x16x32_bf16 v[76:79], v[118:121], v[24:27], v[76:79]
	ds_read_b128 v[118:121], v94 offset:33856
	v_add_u32_e32 v179, v100, v101
	v_add_u32_e32 v100, 0xc0, v95
	s_waitcnt lgkmcnt(0)
	v_mfma_f32_16x16x32_bf16 v[72:75], v[118:121], v[24:27], v[72:75]
	ds_read_b128 v[118:121], v94 offset:42304
	v_add_u32_e32 v180, v100, v97
	v_add_u32_e32 v181, v100, v103
	s_waitcnt lgkmcnt(0)
	v_mfma_f32_16x16x32_bf16 v[68:71], v[118:121], v[24:27], v[68:71]
	ds_read_b128 v[118:121], v94 offset:50752
	v_add_u32_e32 v182, v100, v106
	v_add_u32_e32 v183, v100, v108
	s_waitcnt lgkmcnt(0)
	v_mfma_f32_16x16x32_bf16 v[64:67], v[118:121], v[24:27], v[64:67]
	ds_read_b128 v[118:121], v94 offset:59200
	v_add_u32_e32 v184, v100, v107
	v_add_u32_e32 v185, v100, v105
	s_waitcnt lgkmcnt(0)
	v_mfma_f32_16x16x32_bf16 v[60:63], v[118:121], v[24:27], v[60:63]
	ds_read_b128 v[118:121], v164
	v_add_u32_e32 v186, v100, v104
	v_add_u32_e32 v187, v100, v101
	s_waitcnt lgkmcnt(0)
	v_mfma_f32_16x16x32_bf16 v[28:31], v[118:121], v[24:27], v[28:31]
	ds_read_b128 v[118:121], v165
	v_add_u32_e32 v100, 0x100, v95
	v_add_u32_e32 v188, v100, v97
	s_waitcnt lgkmcnt(0)
	v_mfma_f32_16x16x32_bf16 v[32:35], v[118:121], v[24:27], v[32:35]
	ds_read_b128 v[118:121], v166
	v_add_u32_e32 v189, v100, v103
	v_add_u32_e32 v190, v100, v106
	s_waitcnt lgkmcnt(0)
	v_mfma_f32_16x16x32_bf16 v[118:121], v[118:121], v[24:27], v[44:47]
	s_nop 2
	ds_read_b128 v[44:47], v167
	v_add_u32_e32 v191, v100, v108
	v_add_u32_e32 v192, v100, v107
	s_waitcnt lgkmcnt(0)
	v_mfma_f32_16x16x32_bf16 v[56:59], v[44:47], v[24:27], v[56:59]
	ds_read_b128 v[44:47], v168
	v_add_u32_e32 v195, v100, v101
	v_add_u32_e32 v193, v100, v105
	s_waitcnt lgkmcnt(0)
	v_mfma_f32_16x16x32_bf16 v[52:55], v[44:47], v[24:27], v[52:55]
	ds_read_b128 v[44:47], v169
	v_add_u32_e32 v194, v100, v104
	v_add_u32_e32 v100, 0x140, v95
	s_waitcnt lgkmcnt(0)
	v_mfma_f32_16x16x32_bf16 v[122:125], v[44:47], v[24:27], v[48:51]
	ds_read_b128 v[44:47], v170
	v_add_u32_e32 v199, v100, v97
	v_add_u32_e32 v196, v100, v103
	s_waitcnt lgkmcnt(0)
	v_mfma_f32_16x16x32_bf16 v[130:133], v[44:47], v[24:27], v[40:43]
	s_nop 2
	ds_read_b128 v[40:43], v171
	v_add_u32_e32 v197, v100, v106
	v_add_u32_e32 v198, v100, v108
	s_waitcnt lgkmcnt(0)
	v_mfma_f32_16x16x32_bf16 v[134:137], v[40:43], v[24:27], v[36:39]
	ds_read_b128 v[24:27], v94 offset:128
	v_add_u32_e32 v200, v100, v107
	v_add_u32_e32 v201, v100, v105
	s_waitcnt vmcnt(5) lgkmcnt(0)
	v_mfma_f32_16x16x32_bf16 v[110:113], v[24:27], v[20:23], v[110:113]
	ds_read_b128 v[24:27], v94 offset:8576
	v_add_u32_e32 v202, v100, v104
	v_add_u32_e32 v203, v100, v101
	s_waitcnt lgkmcnt(0)
	v_mfma_f32_16x16x32_bf16 v[114:117], v[24:27], v[20:23], v[114:117]
	ds_read_b128 v[24:27], v94 offset:17024
	v_add_u32_e32 v100, 0x180, v95
	v_add_u32_e32 v209, v100, v97
	s_waitcnt lgkmcnt(0)
	v_mfma_f32_16x16x32_bf16 v[80:83], v[24:27], v[20:23], v[80:83]
	ds_read_b128 v[24:27], v94 offset:25472
	v_add_u32_e32 v211, v100, v103
	v_add_u32_e32 v215, v100, v106
	s_waitcnt lgkmcnt(0)
	v_mfma_f32_16x16x32_bf16 v[76:79], v[24:27], v[20:23], v[76:79]
	ds_read_b128 v[24:27], v94 offset:33920
	v_add_u32_e32 v216, v100, v108
	v_add_u32_e32 v217, v100, v107
	s_waitcnt lgkmcnt(0)
	v_mfma_f32_16x16x32_bf16 v[72:75], v[24:27], v[20:23], v[72:75]
	ds_read_b128 v[24:27], v94 offset:42368
	v_add_u32_e32 v218, v100, v105
	v_add_u32_e32 v219, v100, v104
	s_waitcnt lgkmcnt(0)
	v_mfma_f32_16x16x32_bf16 v[68:71], v[24:27], v[20:23], v[68:71]
	ds_read_b128 v[24:27], v94 offset:50816
	v_add_u32_e32 v220, v100, v101
	v_add_u32_e32 v95, 0x1c0, v95
	s_waitcnt lgkmcnt(0)
	v_mfma_f32_16x16x32_bf16 v[64:67], v[24:27], v[20:23], v[64:67]
	ds_read_b128 v[24:27], v94 offset:59264
	v_add_u32_e32 v205, v95, v97
	v_add_u32_e32 v214, v95, v101
	s_waitcnt lgkmcnt(0)
; #define LAS __attribute__((address_space(3)))
; #define MFMA16(a, b, c) __builtin_amdgcn_mfma_f32_16x16x32_bf16((a), (b), (c), 0, 0, 0)
; __device__ __forceinline__ void xattn_pair(LAS unsigned char* lds, int bh, size_t row_base, bf16* QO, const bf16* Kx, const bf16* VTx, int tid, const WsRef& wsr) {
;     ...
; #pragma unroll
;         for (int kk = 0; kk < 8; ++kk)
; #pragma unroll
;             for (int n = 0; n < 16; ++n) { const bf16x8 kf = *(const LAS bf16x8*)(T + (n * 16 + fr) * LDX + kk * 32 + fq * 8); sx[n] = MFMA16(kf, qf[kk], sx[n]); }
	v_mfma_f32_16x16x32_bf16 v[60:63], v[24:27], v[20:23], v[60:63]
	ds_read_b128 v[24:27], v172
	v_add_u32_e32 v206, v95, v103
	v_add_u32_e32 v207, v95, v106
	s_waitcnt lgkmcnt(0)
	v_mfma_f32_16x16x32_bf16 v[48:51], v[24:27], v[20:23], v[28:31]
	ds_read_b128 v[24:27], v173
	v_add_u32_e32 v208, v95, v108
	v_add_u32_e32 v210, v95, v107
	s_waitcnt lgkmcnt(0)
	v_mfma_f32_16x16x32_bf16 v[44:47], v[24:27], v[20:23], v[32:35]
	ds_read_b128 v[24:27], v174
	v_add_u32_e32 v212, v95, v105
	v_add_u32_e32 v213, v95, v104
	s_waitcnt lgkmcnt(0)
	v_mfma_f32_16x16x32_bf16 v[40:43], v[24:27], v[20:23], v[118:121]
	ds_read_b128 v[24:27], v175
	s_mov_b32 s8, 0xff61b1e6
	s_waitcnt lgkmcnt(0)
	v_mfma_f32_16x16x32_bf16 v[36:39], v[24:27], v[20:23], v[56:59]
	ds_read_b128 v[24:27], v176
	s_nop 1
	ds_read_b128 v[56:59], v94 offset:8640
	s_waitcnt lgkmcnt(1)
	v_mfma_f32_16x16x32_bf16 v[32:35], v[24:27], v[20:23], v[52:55]
	ds_read_b128 v[24:27], v177
	s_nop 1
	ds_read_b128 v[52:55], v179
	s_waitcnt lgkmcnt(1)
	v_mfma_f32_16x16x32_bf16 v[28:31], v[24:27], v[20:23], v[122:125]
	ds_read_b128 v[24:27], v178
	s_waitcnt lgkmcnt(0)
	v_mfma_f32_16x16x32_bf16 v[24:27], v[24:27], v[20:23], v[130:133]
	v_mfma_f32_16x16x32_bf16 v[20:23], v[52:55], v[20:23], v[134:137]
	ds_read_b128 v[52:55], v94 offset:192
	s_waitcnt vmcnt(4) lgkmcnt(0)
	v_mfma_f32_16x16x32_bf16 v[52:55], v[52:55], v[16:19], v[110:113]
	s_nop 2
	ds_read_b128 v[110:113], v94 offset:17088
	s_waitcnt lgkmcnt(0)
	v_mfma_f32_16x16x32_bf16 v[80:83], v[110:113], v[16:19], v[80:83]
	ds_read_b128 v[110:113], v94 offset:25536
	s_waitcnt lgkmcnt(0)
	v_mfma_f32_16x16x32_bf16 v[76:79], v[110:113], v[16:19], v[76:79]
	ds_read_b128 v[110:113], v94 offset:33984
	s_waitcnt lgkmcnt(0)
	v_mfma_f32_16x16x32_bf16 v[72:75], v[110:113], v[16:19], v[72:75]
	ds_read_b128 v[110:113], v94 offset:42432
	s_waitcnt lgkmcnt(0)
	v_mfma_f32_16x16x32_bf16 v[68:71], v[110:113], v[16:19], v[68:71]
	ds_read_b128 v[110:113], v94 offset:50880
	s_waitcnt lgkmcnt(0)
	v_mfma_f32_16x16x32_bf16 v[64:67], v[110:113], v[16:19], v[64:67]
	ds_read_b128 v[110:113], v94 offset:59328
	s_waitcnt lgkmcnt(0)
	v_mfma_f32_16x16x32_bf16 v[60:63], v[110:113], v[16:19], v[60:63]
	ds_read_b128 v[110:113], v180
	s_waitcnt lgkmcnt(0)
	v_mfma_f32_16x16x32_bf16 v[48:51], v[110:113], v[16:19], v[48:51]
	ds_read_b128 v[110:113], v181
	s_waitcnt lgkmcnt(0)
	v_mfma_f32_16x16x32_bf16 v[44:47], v[110:113], v[16:19], v[44:47]
	ds_read_b128 v[110:113], v182
	s_waitcnt lgkmcnt(0)
	v_mfma_f32_16x16x32_bf16 v[110:113], v[110:113], v[16:19], v[40:43]
	s_nop 2
	ds_read_b128 v[40:43], v183
	v_mfma_f32_16x16x32_bf16 v[56:59], v[56:59], v[16:19], v[114:117]
	s_waitcnt lgkmcnt(0)
	v_mfma_f32_16x16x32_bf16 v[114:117], v[40:43], v[16:19], v[36:39]
	s_nop 2
	ds_read_b128 v[36:39], v184
	s_waitcnt lgkmcnt(0)
	v_mfma_f32_16x16x32_bf16 v[118:121], v[36:39], v[16:19], v[32:35]
	s_nop 2
	ds_read_b128 v[32:35], v185
	s_waitcnt lgkmcnt(0)
	v_mfma_f32_16x16x32_bf16 v[122:125], v[32:35], v[16:19], v[28:31]
	s_nop 2
	ds_read_b128 v[28:31], v186
	s_waitcnt lgkmcnt(0)
	v_mfma_f32_16x16x32_bf16 v[130:133], v[28:31], v[16:19], v[24:27]
	s_nop 2
	ds_read_b128 v[24:27], v187
	s_waitcnt lgkmcnt(0)
	v_mfma_f32_16x16x32_bf16 v[134:137], v[24:27], v[16:19], v[20:23]
	ds_read_b128 v[16:19], v94 offset:256
	s_waitcnt vmcnt(3) lgkmcnt(0)
	v_mfma_f32_16x16x32_bf16 v[52:55], v[16:19], v[12:15], v[52:55]
	ds_read_b128 v[16:19], v94 offset:8704
	s_waitcnt lgkmcnt(0)
	v_mfma_f32_16x16x32_bf16 v[56:59], v[16:19], v[12:15], v[56:59]
	ds_read_b128 v[16:19], v94 offset:17152
	s_waitcnt lgkmcnt(0)
	v_mfma_f32_16x16x32_bf16 v[80:83], v[16:19], v[12:15], v[80:83]
	ds_read_b128 v[16:19], v94 offset:25600
	s_waitcnt lgkmcnt(0)
	v_mfma_f32_16x16x32_bf16 v[76:79], v[16:19], v[12:15], v[76:79]
	ds_read_b128 v[16:19], v94 offset:34048
	s_waitcnt lgkmcnt(0)
	v_mfma_f32_16x16x32_bf16 v[72:75], v[16:19], v[12:15], v[72:75]
	ds_read_b128 v[16:19], v94 offset:42496
	s_waitcnt lgkmcnt(0)
	v_mfma_f32_16x16x32_bf16 v[68:71], v[16:19], v[12:15], v[68:71]
	ds_read_b128 v[16:19], v94 offset:50944
	s_waitcnt lgkmcnt(0)
	v_mfma_f32_16x16x32_bf16 v[64:67], v[16:19], v[12:15], v[64:67]
	ds_read_b128 v[16:19], v94 offset:59392
	s_waitcnt lgkmcnt(0)
	v_mfma_f32_16x16x32_bf16 v[60:63], v[16:19], v[12:15], v[60:63]
	ds_read_b128 v[16:19], v188
	s_waitcnt lgkmcnt(0)
	v_mfma_f32_16x16x32_bf16 v[40:43], v[16:19], v[12:15], v[48:51]
	ds_read_b128 v[16:19], v189
	s_nop 1
	ds_read_b128 v[48:51], v94 offset:8768
	s_waitcnt lgkmcnt(1)
	v_mfma_f32_16x16x32_bf16 v[36:39], v[16:19], v[12:15], v[44:47]
	ds_read_b128 v[16:19], v190
	s_nop 1
	ds_read_b128 v[44:47], v195
	s_waitcnt vmcnt(2) lgkmcnt(2)
	v_mfma_f32_16x16x32_bf16 v[48:51], v[48:51], v[8:11], v[56:59]
	s_nop 2
	ds_read_b128 v[56:59], v94 offset:25664
	s_waitcnt lgkmcnt(2)
	v_mfma_f32_16x16x32_bf16 v[32:35], v[16:19], v[12:15], v[110:113]
	ds_read_b128 v[16:19], v191
	s_waitcnt lgkmcnt(0)
	v_mfma_f32_16x16x32_bf16 v[28:31], v[16:19], v[12:15], v[114:117]
	ds_read_b128 v[16:19], v192
	s_waitcnt lgkmcnt(0)
	v_mfma_f32_16x16x32_bf16 v[24:27], v[16:19], v[12:15], v[118:121]
	ds_read_b128 v[16:19], v193
	s_waitcnt lgkmcnt(0)
	v_mfma_f32_16x16x32_bf16 v[20:23], v[16:19], v[12:15], v[122:125]
	ds_read_b128 v[16:19], v194
	s_waitcnt lgkmcnt(0)
	v_mfma_f32_16x16x32_bf16 v[16:19], v[16:19], v[12:15], v[130:133]
	v_mfma_f32_16x16x32_bf16 v[12:15], v[44:47], v[12:15], v[134:137]
	ds_read_b128 v[44:47], v94 offset:320
	v_mfma_f32_16x16x32_bf16 v[56:59], v[56:59], v[8:11], v[76:79]
	s_nop 2
	ds_read_b128 v[76:79], v94 offset:34112
	s_waitcnt lgkmcnt(1)
; #define LAS __attribute__((address_space(3)))
; #define MFMA16(a, b, c) __builtin_amdgcn_mfma_f32_16x16x32_bf16((a), (b), (c), 0, 0, 0)
; __device__ __forceinline__ void xattn_pair(LAS unsigned char* lds, int bh, size_t row_base, bf16* QO, const bf16* Kx, const bf16* VTx, int tid, const WsRef& wsr) {
;     ...
; #pragma unroll
;         for (int kk = 0; kk < 8; ++kk)
; #pragma unroll
;             for (int n = 0; n < 16; ++n) { const bf16x8 kf = *(const LAS bf16x8*)(T + (n * 16 + fr) * LDX + kk * 32 + fq * 8); sx[n] = MFMA16(kf, qf[kk], sx[n]); }
	v_mfma_f32_16x16x32_bf16 v[44:47], v[44:47], v[8:11], v[52:55]
	s_nop 2
	ds_read_b128 v[52:55], v94 offset:17216
	s_waitcnt lgkmcnt(1)
	v_mfma_f32_16x16x32_bf16 v[72:75], v[76:79], v[8:11], v[72:75]
	ds_read_b128 v[76:79], v94 offset:42560
	s_waitcnt lgkmcnt(0)
	v_mfma_f32_16x16x32_bf16 v[68:71], v[76:79], v[8:11], v[68:71]
	ds_read_b128 v[76:79], v94 offset:51008
	s_waitcnt lgkmcnt(0)
	v_mfma_f32_16x16x32_bf16 v[64:67], v[76:79], v[8:11], v[64:67]
	ds_read_b128 v[76:79], v94 offset:59456
	s_waitcnt lgkmcnt(0)
	v_mfma_f32_16x16x32_bf16 v[60:63], v[76:79], v[8:11], v[60:63]
	ds_read_b128 v[76:79], v199
	s_waitcnt lgkmcnt(0)
	v_mfma_f32_16x16x32_bf16 v[40:43], v[76:79], v[8:11], v[40:43]
	ds_read_b128 v[76:79], v196
	s_waitcnt lgkmcnt(0)
	v_mfma_f32_16x16x32_bf16 v[36:39], v[76:79], v[8:11], v[36:39]
	ds_read_b128 v[76:79], v197
	s_waitcnt lgkmcnt(0)
	v_mfma_f32_16x16x32_bf16 v[32:35], v[76:79], v[8:11], v[32:35]
	ds_read_b128 v[76:79], v198
	s_waitcnt lgkmcnt(0)
	v_mfma_f32_16x16x32_bf16 v[28:31], v[76:79], v[8:11], v[28:31]
	ds_read_b128 v[76:79], v200
	s_waitcnt lgkmcnt(0)
	v_mfma_f32_16x16x32_bf16 v[24:27], v[76:79], v[8:11], v[24:27]
	ds_read_b128 v[76:79], v201
	s_waitcnt lgkmcnt(0)
	v_mfma_f32_16x16x32_bf16 v[20:23], v[76:79], v[8:11], v[20:23]
	ds_read_b128 v[76:79], v202
	s_waitcnt lgkmcnt(0)
	v_mfma_f32_16x16x32_bf16 v[16:19], v[76:79], v[8:11], v[16:19]
	ds_read_b128 v[76:79], v203
	v_mfma_f32_16x16x32_bf16 v[52:55], v[52:55], v[8:11], v[80:83]
	s_waitcnt lgkmcnt(0)
	v_mfma_f32_16x16x32_bf16 v[8:11], v[76:79], v[8:11], v[12:15]
	s_nop 2
	ds_read_b128 v[12:15], v94 offset:384
	s_waitcnt vmcnt(1) lgkmcnt(0)
	v_mfma_f32_16x16x32_bf16 v[12:15], v[12:15], v[4:7], v[44:47]
	s_nop 2
	ds_read_b128 v[44:47], v94 offset:8832
	s_waitcnt lgkmcnt(0)
	v_mfma_f32_16x16x32_bf16 v[44:47], v[44:47], v[4:7], v[48:51]
	s_nop 2
	ds_read_b128 v[48:51], v94 offset:17280
	s_waitcnt lgkmcnt(0)
	v_mfma_f32_16x16x32_bf16 v[48:51], v[48:51], v[4:7], v[52:55]
	s_nop 2
	ds_read_b128 v[52:55], v94 offset:25728
	s_waitcnt lgkmcnt(0)
	v_mfma_f32_16x16x32_bf16 v[76:79], v[52:55], v[4:7], v[56:59]
	ds_read_b128 v[52:55], v94 offset:34176
	s_waitcnt lgkmcnt(0)
	v_mfma_f32_16x16x32_bf16 v[72:75], v[52:55], v[4:7], v[72:75]
	ds_read_b128 v[52:55], v94 offset:42624
	s_waitcnt lgkmcnt(0)
	v_mfma_f32_16x16x32_bf16 v[68:71], v[52:55], v[4:7], v[68:71]
	ds_read_b128 v[52:55], v94 offset:51072
	s_waitcnt lgkmcnt(0)
	v_mfma_f32_16x16x32_bf16 v[64:67], v[52:55], v[4:7], v[64:67]
	ds_read_b128 v[52:55], v94 offset:59520
	s_waitcnt lgkmcnt(0)
	v_mfma_f32_16x16x32_bf16 v[80:83], v[52:55], v[4:7], v[60:63]
	ds_read_b128 v[52:55], v209
	s_waitcnt lgkmcnt(0)
	v_mfma_f32_16x16x32_bf16 v[110:113], v[52:55], v[4:7], v[40:43]
	s_nop 2
	ds_read_b128 v[40:43], v211
	s_waitcnt lgkmcnt(0)
	v_mfma_f32_16x16x32_bf16 v[114:117], v[40:43], v[4:7], v[36:39]
	s_nop 2
	ds_read_b128 v[36:39], v215
	s_waitcnt lgkmcnt(0)
	v_mfma_f32_16x16x32_bf16 v[118:121], v[36:39], v[4:7], v[32:35]
	s_nop 2
	ds_read_b128 v[32:35], v216
	s_waitcnt lgkmcnt(0)
	v_mfma_f32_16x16x32_bf16 v[122:125], v[32:35], v[4:7], v[28:31]
	s_nop 2
	ds_read_b128 v[28:31], v217
	s_waitcnt lgkmcnt(0)
	v_mfma_f32_16x16x32_bf16 v[130:133], v[28:31], v[4:7], v[24:27]
	s_nop 2
	ds_read_b128 v[24:27], v218
	s_waitcnt lgkmcnt(0)
	v_mfma_f32_16x16x32_bf16 v[134:137], v[24:27], v[4:7], v[20:23]
	s_nop 2
	ds_read_b128 v[20:23], v219
	s_waitcnt lgkmcnt(0)
	v_mfma_f32_16x16x32_bf16 v[138:141], v[20:23], v[4:7], v[16:19]
	s_nop 2
	ds_read_b128 v[16:19], v220
	s_waitcnt lgkmcnt(0)
	v_mfma_f32_16x16x32_bf16 v[142:145], v[16:19], v[4:7], v[8:11]
	ds_read_b128 v[4:7], v94 offset:448
	s_waitcnt vmcnt(0) lgkmcnt(0)
	v_mfma_f32_16x16x32_bf16 v[60:63], v[4:7], v[0:3], v[12:15]
	ds_read_b128 v[4:7], v94 offset:8896
	s_waitcnt lgkmcnt(0)
	v_mfma_f32_16x16x32_bf16 v[56:59], v[4:7], v[0:3], v[44:47]
	ds_read_b128 v[4:7], v94 offset:17344
	s_waitcnt lgkmcnt(0)
	v_mfma_f32_16x16x32_bf16 v[52:55], v[4:7], v[0:3], v[48:51]
	ds_read_b128 v[4:7], v94 offset:25792
	s_waitcnt lgkmcnt(0)
	v_mfma_f32_16x16x32_bf16 v[48:51], v[4:7], v[0:3], v[76:79]
	ds_read_b128 v[4:7], v94 offset:34240
	s_waitcnt lgkmcnt(0)
	v_mfma_f32_16x16x32_bf16 v[44:47], v[4:7], v[0:3], v[72:75]
	ds_read_b128 v[4:7], v94 offset:42688
	s_waitcnt lgkmcnt(0)
	v_mfma_f32_16x16x32_bf16 v[40:43], v[4:7], v[0:3], v[68:71]
	ds_read_b128 v[4:7], v94 offset:51136
	s_waitcnt lgkmcnt(0)
	v_mfma_f32_16x16x32_bf16 v[36:39], v[4:7], v[0:3], v[64:67]
	ds_read_b128 v[4:7], v94 offset:59584
	s_nop 1
	ds_read_b128 v[64:67], v214
	s_waitcnt lgkmcnt(1)
	v_mfma_f32_16x16x32_bf16 v[32:35], v[4:7], v[0:3], v[80:83]
	ds_read_b128 v[4:7], v205
	s_waitcnt lgkmcnt(0)
	v_mfma_f32_16x16x32_bf16 v[28:31], v[4:7], v[0:3], v[110:113]
	ds_read_b128 v[4:7], v206
	s_waitcnt lgkmcnt(0)
	v_mfma_f32_16x16x32_bf16 v[24:27], v[4:7], v[0:3], v[114:117]
	ds_read_b128 v[4:7], v207
	s_waitcnt lgkmcnt(0)
	v_mfma_f32_16x16x32_bf16 v[20:23], v[4:7], v[0:3], v[118:121]
	ds_read_b128 v[4:7], v208
	s_waitcnt lgkmcnt(0)
	v_mfma_f32_16x16x32_bf16 v[16:19], v[4:7], v[0:3], v[122:125]
	ds_read_b128 v[4:7], v210
	s_waitcnt lgkmcnt(0)
	v_mfma_f32_16x16x32_bf16 v[12:15], v[4:7], v[0:3], v[130:133]
	ds_read_b128 v[4:7], v212
	s_waitcnt lgkmcnt(0)
	v_mfma_f32_16x16x32_bf16 v[8:11], v[4:7], v[0:3], v[134:137]
	ds_read_b128 v[4:7], v213
	s_waitcnt lgkmcnt(0)
; #define LAS __attribute__((address_space(3)))
; __device__ __forceinline__ float fexp2(float x) { return __builtin_amdgcn_exp2f(x); }
; #define MFMA16(a, b, c) __builtin_amdgcn_mfma_f32_16x16x32_bf16((a), (b), (c), 0, 0, 0)
; __device__ __forceinline__ void xattn_softmax(f32x4 (&s)[16], bf16x8 (&pf)[8], float& rinv) {
;     float mx = -3.0e38f;
; #pragma unroll
;     for (int n = 0; n < 16; ++n) mx = fmaxf(mx, fmaxf(fmaxf(s[n][0], s[n][1]), fmaxf(s[n][2], s[n][3])));
;     mx = fmaxf(mx, __shfl_xor(mx, 16)); mx = fmaxf(mx, __shfl_xor(mx, 32));
;     const float sc = 0.0625f * LOG2E; float sum = 0.f;
; #pragma unroll
;     for (int n = 0; n < 16; ++n)
; #pragma unroll
;         for (int r = 0; r < 4; ++r) { const float p = fexp2((s[n][r] - mx) * sc); s[n][r] = p; sum += p; }
; __device__ __forceinline__ void xattn_pair(LAS unsigned char* lds, int bh, size_t row_base, bf16* QO, const bf16* Kx, const bf16* VTx, int tid, const WsRef& wsr) {
;     ...
;             for (int n = 0; n < 16; ++n) { const bf16x8 kf = *(const LAS bf16x8*)(T + (n * 16 + fr) * LDX + kk * 32 + fq * 8); sx[n] = MFMA16(kf, qf[kk], sx[n]); }
;         if (half == 0) xattn_softmax(sx, pf0, rinv0); else xattn_softmax(sx, pf1, rinv1);
	v_mfma_f32_16x16x32_bf16 v[4:7], v[4:7], v[0:3], v[138:141]
	v_mfma_f32_16x16x32_bf16 v[0:3], v[64:67], v[0:3], v[142:145]
	v_max_f32_e32 v64, v63, v63
	v_max_f32_e32 v65, v62, v62
	v_max_f32_e32 v64, v65, v64
	v_max_f32_e32 v65, v59, v59
	v_max_f32_e32 v66, v58, v58
	v_max_f32_e32 v65, v66, v65
	v_max3_f32 v64, v60, v61, v64
	v_max3_f32 v65, v56, v57, v65
	v_max3_f32 v64, v64, s8, v65
	v_max_f32_e32 v65, v55, v55
	v_max_f32_e32 v66, v54, v54
	v_max_f32_e32 v65, v66, v65
	v_max_f32_e32 v66, v51, v51
	v_max_f32_e32 v67, v50, v50
	v_max_f32_e32 v66, v67, v66
	v_max3_f32 v65, v52, v53, v65
	v_max3_f32 v66, v48, v49, v66
	v_max3_f32 v64, v64, v65, v66
	v_max_f32_e32 v65, v47, v47
	v_max_f32_e32 v66, v46, v46
	v_max_f32_e32 v65, v66, v65
	v_max_f32_e32 v66, v43, v43
	v_max_f32_e32 v67, v42, v42
	v_max_f32_e32 v66, v67, v66
	v_max3_f32 v65, v44, v45, v65
	v_max3_f32 v66, v40, v41, v66
	v_max3_f32 v64, v64, v65, v66
	v_max_f32_e32 v65, v39, v39
	v_max_f32_e32 v66, v38, v38
	v_max_f32_e32 v65, v66, v65
	v_max_f32_e32 v66, v35, v35
	v_max_f32_e32 v67, v34, v34
	v_max_f32_e32 v66, v67, v66
	v_max3_f32 v65, v36, v37, v65
	v_max3_f32 v66, v32, v33, v66
	v_max3_f32 v64, v64, v65, v66
	v_max_f32_e32 v65, v31, v31
	v_max_f32_e32 v66, v30, v30
	v_max_f32_e32 v65, v66, v65
	v_max_f32_e32 v66, v27, v27
	v_max_f32_e32 v67, v26, v26
	v_max_f32_e32 v66, v67, v66
	v_max3_f32 v65, v28, v29, v65
	v_max3_f32 v66, v24, v25, v66
	v_max3_f32 v64, v64, v65, v66
	v_max_f32_e32 v65, v23, v23
	v_max_f32_e32 v66, v22, v22
	v_max_f32_e32 v65, v66, v65
	v_max_f32_e32 v66, v19, v19
	v_max_f32_e32 v67, v18, v18
	v_max_f32_e32 v66, v67, v66
	v_max3_f32 v65, v20, v21, v65
	v_max3_f32 v66, v16, v17, v66
	v_max3_f32 v64, v64, v65, v66
	v_max_f32_e32 v65, v15, v15
	v_max_f32_e32 v66, v14, v14
	v_max_f32_e32 v65, v66, v65
	v_max_f32_e32 v66, v11, v11
	v_max_f32_e32 v67, v10, v10
	v_max_f32_e32 v66, v67, v66
	v_max3_f32 v65, v12, v13, v65
	v_max3_f32 v66, v8, v9, v66
	v_max3_f32 v64, v64, v65, v66
	v_max_f32_e32 v65, v7, v7
	v_max_f32_e32 v66, v6, v6
	v_max_f32_e32 v65, v66, v65
	v_max_f32_e32 v66, v3, v3
	v_max_f32_e32 v67, v2, v2
	v_max_f32_e32 v66, v67, v66
	v_max3_f32 v65, v4, v5, v65
	v_max3_f32 v66, v0, v1, v66
	v_max3_f32 v64, v64, v65, v66
	v_mbcnt_lo_u32_b32 v65, -1, 0
	v_mbcnt_hi_u32_b32 v65, -1, v65
	v_and_b32_e32 v67, 64, v65
	v_xor_b32_e32 v66, 16, v65
	v_add_u32_e32 v67, 64, v67
	v_cmp_lt_i32_e32 vcc, v66, v67
	s_nop 1
	v_cndmask_b32_e32 v66, v65, v66, vcc
	v_lshlrev_b32_e32 v155, 2, v66
	ds_bpermute_b32 v66, v155, v64
	s_waitcnt lgkmcnt(0)
	v_max_f32_e32 v66, v66, v66
	v_max_f32_e32 v66, v64, v66
	v_xor_b32_e32 v64, 32, v65
	v_cmp_lt_i32_e32 vcc, v64, v67
	s_nop 1
	v_cndmask_b32_e32 v64, v65, v64, vcc
	v_lshlrev_b32_e32 v64, 2, v64
	ds_bpermute_b32 v65, v64, v66
	s_waitcnt lgkmcnt(0)
	v_max_f32_e32 v65, v65, v65
	v_max_f32_e32 v147, v66, v65
	v_sub_f32_e32 v61, v61, v147
	v_sub_f32_e32 v60, v60, v147
	v_mul_f32_e32 v61, 0x3db8aa3b, v61
	v_mul_f32_e32 v60, 0x3db8aa3b, v60
	v_exp_f32_e32 v136, v61
	v_sub_f32_e32 v61, v62, v147
	v_exp_f32_e32 v133, v60
	v_mul_f32_e32 v61, 0x3db8aa3b, v61
	v_exp_f32_e32 v140, v61
	v_sub_f32_e32 v61, v63, v147
	v_sub_f32_e32 v57, v57, v147
	v_mul_f32_e32 v61, 0x3db8aa3b, v61
	v_sub_f32_e32 v56, v56, v147
	v_mul_f32_e32 v57, 0x3db8aa3b, v57
	v_exp_f32_e32 v144, v61
	v_mul_f32_e32 v56, 0x3db8aa3b, v56
	v_exp_f32_e32 v150, v57
	v_sub_f32_e32 v57, v58, v147
	v_add_f32_e32 v60, 0, v133
	v_exp_f32_e32 v149, v56
	v_mul_f32_e32 v57, 0x3db8aa3b, v57
	v_add_f32_e32 v60, v136, v60
	v_exp_f32_e32 v151, v57
	v_sub_f32_e32 v57, v59, v147
	v_sub_f32_e32 v53, v53, v147
	v_add_f32_e32 v60, v140, v60
	v_mul_f32_e32 v57, 0x3db8aa3b, v57
	v_sub_f32_e32 v52, v52, v147
	v_mul_f32_e32 v53, 0x3db8aa3b, v53
	v_add_f32_e32 v60, v144, v60
	v_exp_f32_e32 v152, v57
	v_mul_f32_e32 v52, 0x3db8aa3b, v52
	v_exp_f32_e32 v123, v53
	v_sub_f32_e32 v53, v54, v147
	v_add_f32_e32 v56, v149, v60
	v_exp_f32_e32 v118, v52
	v_mul_f32_e32 v53, 0x3db8aa3b, v53
	v_add_f32_e32 v56, v150, v56
	v_exp_f32_e32 v127, v53
	v_sub_f32_e32 v53, v55, v147
	v_sub_f32_e32 v49, v49, v147
	v_add_f32_e32 v56, v151, v56
	v_mul_f32_e32 v53, 0x3db8aa3b, v53
	v_sub_f32_e32 v48, v48, v147
	v_mul_f32_e32 v49, 0x3db8aa3b, v49
	v_add_f32_e32 v56, v152, v56
	v_exp_f32_e32 v132, v53
	v_mul_f32_e32 v48, 0x3db8aa3b, v48
	v_exp_f32_e32 v143, v49
	v_sub_f32_e32 v49, v50, v147
	v_add_f32_e32 v52, v118, v56
	v_exp_f32_e32 v139, v48
	v_mul_f32_e32 v49, 0x3db8aa3b, v49
	v_add_f32_e32 v52, v123, v52
	v_exp_f32_e32 v146, v49
	v_sub_f32_e32 v49, v51, v147
	v_sub_f32_e32 v45, v45, v147
	v_add_f32_e32 v52, v127, v52
	v_mul_f32_e32 v49, 0x3db8aa3b, v49
	v_sub_f32_e32 v44, v44, v147
	v_mul_f32_e32 v45, 0x3db8aa3b, v45
	v_add_f32_e32 v52, v132, v52
	v_exp_f32_e32 v148, v49
	v_mul_f32_e32 v44, 0x3db8aa3b, v44
	v_exp_f32_e32 v114, v45
	v_sub_f32_e32 v45, v46, v147
	v_add_f32_e32 v48, v139, v52
	v_exp_f32_e32 v111, v44
	v_mul_f32_e32 v45, 0x3db8aa3b, v45
	v_add_f32_e32 v48, v143, v48
	v_exp_f32_e32 v117, v45
	v_sub_f32_e32 v45, v47, v147
	v_sub_f32_e32 v41, v41, v147
	v_add_f32_e32 v48, v146, v48
	v_mul_f32_e32 v45, 0x3db8aa3b, v45
	v_sub_f32_e32 v40, v40, v147
	v_mul_f32_e32 v41, 0x3db8aa3b, v41
	v_add_f32_e32 v48, v148, v48
	v_exp_f32_e32 v122, v45
	v_mul_f32_e32 v40, 0x3db8aa3b, v40
	v_exp_f32_e32 v135, v41
	v_sub_f32_e32 v41, v42, v147
	v_add_f32_e32 v44, v111, v48
	v_exp_f32_e32 v130, v40
	v_mul_f32_e32 v41, 0x3db8aa3b, v41
	v_add_f32_e32 v44, v114, v44
	v_exp_f32_e32 v138, v41
	v_sub_f32_e32 v41, v43, v147
	v_sub_f32_e32 v37, v37, v147
	v_add_f32_e32 v44, v117, v44
	v_mul_f32_e32 v41, 0x3db8aa3b, v41
	v_sub_f32_e32 v36, v36, v147
; #define LAS __attribute__((address_space(3)))
; __device__ __forceinline__ float fexp2(float x) { return __builtin_amdgcn_exp2f(x); }
; #define MFMA16(a, b, c) __builtin_amdgcn_mfma_f32_16x16x32_bf16((a), (b), (c), 0, 0, 0)
; __device__ __forceinline__ void xattn_softmax(f32x4 (&s)[16], bf16x8 (&pf)[8], float& rinv) {
;     ...
;         for (int r = 0; r < 4; ++r) { const float p = fexp2((s[n][r] - mx) * sc); s[n][r] = p; sum += p; }
;     sum += __shfl_xor(sum, 16); sum += __shfl_xor(sum, 32);
; __device__ __forceinline__ void xattn_pair(LAS unsigned char* lds, int bh, size_t row_base, bf16* QO, const bf16* Kx, const bf16* VTx, int tid, const WsRef& wsr) {
;     ...
;         const bf16* qp = half ? qp1 : qp0;
;         bf16x8 qf[8];
; #pragma unroll
;         for (int kk = 0; kk < 8; ++kk) qf[kk] = *(const bf16x8*)(qp + kk * 32 + fq * 8);
;         f32x4 sx[16];
; #pragma unroll
;         for (int n = 0; n < 16; ++n) sx[n] = (f32x4){0.f, 0.f, 0.f, 0.f};
; #pragma unroll
;         for (int kk = 0; kk < 8; ++kk)
; #pragma unroll
;             for (int n = 0; n < 16; ++n) { const bf16x8 kf = *(const LAS bf16x8*)(T + (n * 16 + fr) * LDX + kk * 32 + fq * 8); sx[n] = MFMA16(kf, qf[kk], sx[n]); }
	v_mul_f32_e32 v37, 0x3db8aa3b, v37
	v_add_f32_e32 v44, v122, v44
	v_exp_f32_e32 v142, v41
	v_mul_f32_e32 v36, 0x3db8aa3b, v36
	v_exp_f32_e32 v102, v37
	v_sub_f32_e32 v37, v38, v147
	v_add_f32_e32 v40, v130, v44
	v_exp_f32_e32 v83, v36
	v_mul_f32_e32 v37, 0x3db8aa3b, v37
	v_add_f32_e32 v40, v135, v40
	v_exp_f32_e32 v110, v37
	v_sub_f32_e32 v37, v39, v147
	v_sub_f32_e32 v33, v33, v147
	v_add_f32_e32 v40, v138, v40
	v_mul_f32_e32 v37, 0x3db8aa3b, v37
	v_sub_f32_e32 v32, v32, v147
	v_mul_f32_e32 v33, 0x3db8aa3b, v33
	v_add_f32_e32 v40, v142, v40
	v_exp_f32_e32 v113, v37
	v_mul_f32_e32 v32, 0x3db8aa3b, v32
	v_exp_f32_e32 v125, v33
	v_sub_f32_e32 v33, v34, v147
	v_add_f32_e32 v36, v83, v40
	v_exp_f32_e32 v120, v32
	v_mul_f32_e32 v33, 0x3db8aa3b, v33
	v_add_f32_e32 v36, v102, v36
	v_exp_f32_e32 v129, v33
	v_sub_f32_e32 v33, v35, v147
	v_sub_f32_e32 v29, v29, v147
	v_add_f32_e32 v36, v110, v36
	v_mul_f32_e32 v33, 0x3db8aa3b, v33
	v_sub_f32_e32 v28, v28, v147
	v_mul_f32_e32 v29, 0x3db8aa3b, v29
	v_add_f32_e32 v36, v113, v36
	v_exp_f32_e32 v134, v33
	v_mul_f32_e32 v28, 0x3db8aa3b, v28
	v_exp_f32_e32 v80, v29
	v_sub_f32_e32 v29, v30, v147
	v_add_f32_e32 v32, v120, v36
	v_exp_f32_e32 v78, v28
	v_mul_f32_e32 v29, 0x3db8aa3b, v29
	v_add_f32_e32 v32, v125, v32
	v_exp_f32_e32 v82, v29
	v_sub_f32_e32 v29, v31, v147
	v_sub_f32_e32 v25, v25, v147
	v_add_f32_e32 v32, v129, v32
	v_mul_f32_e32 v29, 0x3db8aa3b, v29
	v_sub_f32_e32 v24, v24, v147
	v_mul_f32_e32 v25, 0x3db8aa3b, v25
	v_add_f32_e32 v32, v134, v32
	v_exp_f32_e32 v100, v29
	v_mul_f32_e32 v24, 0x3db8aa3b, v24
	v_exp_f32_e32 v115, v25
	v_sub_f32_e32 v25, v26, v147
	v_add_f32_e32 v28, v78, v32
	v_exp_f32_e32 v112, v24
	v_mul_f32_e32 v25, 0x3db8aa3b, v25
	v_add_f32_e32 v28, v80, v28
	v_exp_f32_e32 v119, v25
	v_sub_f32_e32 v25, v27, v147
	v_sub_f32_e32 v21, v21, v147
	v_add_f32_e32 v28, v82, v28
	v_mul_f32_e32 v25, 0x3db8aa3b, v25
	v_sub_f32_e32 v20, v20, v147
	v_mul_f32_e32 v21, 0x3db8aa3b, v21
	v_add_f32_e32 v28, v100, v28
	v_exp_f32_e32 v124, v25
	v_mul_f32_e32 v20, 0x3db8aa3b, v20
	v_exp_f32_e32 v69, v21
	v_sub_f32_e32 v21, v22, v147
	v_add_f32_e32 v24, v112, v28
	v_exp_f32_e32 v66, v20
	v_mul_f32_e32 v21, 0x3db8aa3b, v21
	v_add_f32_e32 v24, v115, v24
	v_exp_f32_e32 v71, v21
	v_sub_f32_e32 v21, v23, v147
	v_sub_f32_e32 v17, v17, v147
	v_add_f32_e32 v24, v119, v24
	v_mul_f32_e32 v21, 0x3db8aa3b, v21
	v_sub_f32_e32 v16, v16, v147
	v_mul_f32_e32 v17, 0x3db8aa3b, v17
	v_add_f32_e32 v24, v124, v24
	v_exp_f32_e32 v72, v21
	v_mul_f32_e32 v16, 0x3db8aa3b, v16
	v_exp_f32_e32 v79, v17
	v_sub_f32_e32 v17, v18, v147
	v_add_f32_e32 v20, v66, v24
	v_exp_f32_e32 v77, v16
	v_mul_f32_e32 v17, 0x3db8aa3b, v17
	v_add_f32_e32 v20, v69, v20
	v_exp_f32_e32 v81, v17
	v_sub_f32_e32 v17, v19, v147
	v_sub_f32_e32 v13, v13, v147
	v_add_f32_e32 v20, v71, v20
	v_mul_f32_e32 v17, 0x3db8aa3b, v17
	v_sub_f32_e32 v12, v12, v147
	v_mul_f32_e32 v13, 0x3db8aa3b, v13
	v_add_f32_e32 v20, v72, v20
	v_exp_f32_e32 v95, v17
	v_mul_f32_e32 v12, 0x3db8aa3b, v12
	v_exp_f32_e32 v68, v13
	v_sub_f32_e32 v13, v14, v147
	v_add_f32_e32 v16, v77, v20
	v_exp_f32_e32 v65, v12
	v_mul_f32_e32 v13, 0x3db8aa3b, v13
	v_add_f32_e32 v16, v79, v16
	v_exp_f32_e32 v67, v13
	v_sub_f32_e32 v13, v15, v147
	v_sub_f32_e32 v9, v9, v147
	v_add_f32_e32 v16, v81, v16
	v_mul_f32_e32 v13, 0x3db8aa3b, v13
	v_sub_f32_e32 v8, v8, v147
	v_mul_f32_e32 v9, 0x3db8aa3b, v9
	v_add_f32_e32 v16, v95, v16
	v_exp_f32_e32 v70, v13
	v_mul_f32_e32 v8, 0x3db8aa3b, v8
	v_exp_f32_e32 v76, v9
	v_sub_f32_e32 v9, v10, v147
	v_add_f32_e32 v12, v65, v16
	v_exp_f32_e32 v74, v8
	v_mul_f32_e32 v9, 0x3db8aa3b, v9
	v_add_f32_e32 v12, v68, v12
	v_exp_f32_e32 v73, v9
	v_sub_f32_e32 v9, v11, v147
	v_sub_f32_e32 v5, v5, v147
	v_add_f32_e32 v12, v67, v12
	v_mul_f32_e32 v9, 0x3db8aa3b, v9
	v_sub_f32_e32 v4, v4, v147
	v_mul_f32_e32 v5, 0x3db8aa3b, v5
	v_add_f32_e32 v12, v70, v12
	v_exp_f32_e32 v75, v9
	v_mul_f32_e32 v4, 0x3db8aa3b, v4
	v_exp_f32_e32 v121, v5
	v_sub_f32_e32 v5, v6, v147
	v_add_f32_e32 v8, v74, v12
	v_exp_f32_e32 v116, v4
	v_mul_f32_e32 v5, 0x3db8aa3b, v5
	v_add_f32_e32 v8, v76, v8
	v_exp_f32_e32 v126, v5
	v_sub_f32_e32 v5, v7, v147
	v_sub_f32_e32 v1, v1, v147
	v_add_f32_e32 v8, v73, v8
	v_mul_f32_e32 v5, 0x3db8aa3b, v5
	v_sub_f32_e32 v0, v0, v147
	v_mul_f32_e32 v1, 0x3db8aa3b, v1
	v_add_f32_e32 v8, v75, v8
	v_exp_f32_e32 v131, v5
	v_mul_f32_e32 v0, 0x3db8aa3b, v0
	v_exp_f32_e32 v141, v1
	v_sub_f32_e32 v1, v2, v147
	v_add_f32_e32 v4, v116, v8
	v_exp_f32_e32 v137, v0
	v_mul_f32_e32 v1, 0x3db8aa3b, v1
	v_add_f32_e32 v4, v121, v4
	v_exp_f32_e32 v145, v1
	v_sub_f32_e32 v1, v3, v147
	v_add_f32_e32 v4, v126, v4
	v_mul_f32_e32 v1, 0x3db8aa3b, v1
	v_add_f32_e32 v4, v131, v4
	v_exp_f32_e32 v147, v1
	v_add_f32_e32 v0, v137, v4
	v_add_f32_e32 v0, v141, v0
	v_add_f32_e32 v0, v145, v0
	v_add_f32_e32 v153, v147, v0
	ds_bpermute_b32 v154, v155, v153
	v_lshl_add_u64 v[0:1], v[98:99], 0, v[86:87]
	global_load_dwordx4 v[28:31], v[0:1], off
	global_load_dwordx4 v[24:27], v[0:1], off offset:64
	global_load_dwordx4 v[20:23], v[0:1], off offset:128
	global_load_dwordx4 v[16:19], v[0:1], off offset:192
	global_load_dwordx4 v[12:15], v[0:1], off offset:256
	global_load_dwordx4 v[8:11], v[0:1], off offset:320
	global_load_dwordx4 v[4:7], v[0:1], off offset:384
	s_nop 0
	global_load_dwordx4 v[0:3], v[0:1], off offset:448
	ds_read_b128 v[32:35], v94
	s_waitcnt vmcnt(7) lgkmcnt(0)
	v_mfma_f32_16x16x32_bf16 v[44:47], v[32:35], v[28:31], 0
	ds_read_b128 v[32:35], v94 offset:8448
	s_waitcnt lgkmcnt(0)
	v_mfma_f32_16x16x32_bf16 v[48:51], v[32:35], v[28:31], 0
	ds_read_b128 v[32:35], v94 offset:16896
	s_waitcnt lgkmcnt(0)
; #define LAS __attribute__((address_space(3)))
; #define MFMA16(a, b, c) __builtin_amdgcn_mfma_f32_16x16x32_bf16((a), (b), (c), 0, 0, 0)
; __device__ __forceinline__ void xattn_pair(LAS unsigned char* lds, int bh, size_t row_base, bf16* QO, const bf16* Kx, const bf16* VTx, int tid, const WsRef& wsr) {
;     ...
; #pragma unroll
;         for (int kk = 0; kk < 8; ++kk)
; #pragma unroll
;             for (int n = 0; n < 16; ++n) { const bf16x8 kf = *(const LAS bf16x8*)(T + (n * 16 + fr) * LDX + kk * 32 + fq * 8); sx[n] = MFMA16(kf, qf[kk], sx[n]); }
	v_mfma_f32_16x16x32_bf16 v[52:55], v[32:35], v[28:31], 0
	ds_read_b128 v[32:35], v94 offset:25344
	s_waitcnt lgkmcnt(0)
	v_mfma_f32_16x16x32_bf16 v[56:59], v[32:35], v[28:31], 0
	ds_read_b128 v[32:35], v94 offset:33792
	s_waitcnt lgkmcnt(0)
	v_mfma_f32_16x16x32_bf16 v[60:63], v[32:35], v[28:31], 0
	ds_read_b128 v[32:35], v94 offset:42240
	s_waitcnt lgkmcnt(0)
	v_mfma_f32_16x16x32_bf16 v[222:225], v[32:35], v[28:31], 0
	ds_read_b128 v[32:35], v94 offset:50688
	s_waitcnt lgkmcnt(0)
	v_mfma_f32_16x16x32_bf16 v[226:229], v[32:35], v[28:31], 0
	ds_read_b128 v[32:35], v94 offset:59136
	s_waitcnt lgkmcnt(0)
	v_mfma_f32_16x16x32_bf16 v[230:233], v[32:35], v[28:31], 0
	ds_read_b128 v[32:35], v156
	s_waitcnt lgkmcnt(0)
	v_mfma_f32_16x16x32_bf16 v[234:237], v[32:35], v[28:31], 0
	ds_read_b128 v[32:35], v157
	s_waitcnt lgkmcnt(0)
	v_mfma_f32_16x16x32_bf16 v[238:241], v[32:35], v[28:31], 0
	ds_read_b128 v[32:35], v158
	s_waitcnt lgkmcnt(0)
	v_mfma_f32_16x16x32_bf16 v[242:245], v[32:35], v[28:31], 0
	ds_read_b128 v[32:35], v159
	s_waitcnt lgkmcnt(0)
	v_mfma_f32_16x16x32_bf16 v[156:159], v[32:35], v[28:31], 0
	ds_read_b128 v[32:35], v160
	s_waitcnt lgkmcnt(0)
	v_mfma_f32_16x16x32_bf16 v[40:43], v[32:35], v[28:31], 0
	ds_read_b128 v[32:35], v161
	s_waitcnt lgkmcnt(0)
	v_mfma_f32_16x16x32_bf16 v[36:39], v[32:35], v[28:31], 0
	ds_read_b128 v[32:35], v162
	ds_read_b128 v[160:163], v163
	s_waitcnt lgkmcnt(1)
	v_mfma_f32_16x16x32_bf16 v[32:35], v[32:35], v[28:31], 0
	s_waitcnt lgkmcnt(0)
	v_mfma_f32_16x16x32_bf16 v[28:31], v[160:163], v[28:31], 0
	ds_read_b128 v[160:163], v94 offset:64
	s_waitcnt vmcnt(6) lgkmcnt(0)
	v_mfma_f32_16x16x32_bf16 v[44:47], v[160:163], v[24:27], v[44:47]
	ds_read_b128 v[160:163], v94 offset:8512
	s_waitcnt lgkmcnt(0)
	v_mfma_f32_16x16x32_bf16 v[48:51], v[160:163], v[24:27], v[48:51]
	ds_read_b128 v[160:163], v94 offset:16960
	s_waitcnt lgkmcnt(0)
	v_mfma_f32_16x16x32_bf16 v[52:55], v[160:163], v[24:27], v[52:55]
	ds_read_b128 v[160:163], v94 offset:25408
	s_waitcnt lgkmcnt(0)
	v_mfma_f32_16x16x32_bf16 v[56:59], v[160:163], v[24:27], v[56:59]
	ds_read_b128 v[160:163], v94 offset:33856
	s_waitcnt lgkmcnt(0)
	v_mfma_f32_16x16x32_bf16 v[60:63], v[160:163], v[24:27], v[60:63]
	ds_read_b128 v[160:163], v94 offset:42304
	s_waitcnt lgkmcnt(0)
	v_mfma_f32_16x16x32_bf16 v[160:163], v[160:163], v[24:27], v[222:225]
	s_nop 2
	ds_read_b128 v[222:225], v94 offset:50752
	s_waitcnt lgkmcnt(0)
	v_mfma_f32_16x16x32_bf16 v[222:225], v[222:225], v[24:27], v[226:229]
	s_nop 2
	ds_read_b128 v[226:229], v94 offset:59200
	s_waitcnt lgkmcnt(0)
	v_mfma_f32_16x16x32_bf16 v[226:229], v[226:229], v[24:27], v[230:233]
	s_nop 2
	ds_read_b128 v[230:233], v164
	s_waitcnt lgkmcnt(0)
	v_mfma_f32_16x16x32_bf16 v[230:233], v[230:233], v[24:27], v[234:237]
	s_nop 2
	ds_read_b128 v[234:237], v165
	s_waitcnt lgkmcnt(0)
	v_mfma_f32_16x16x32_bf16 v[234:237], v[234:237], v[24:27], v[238:241]
	s_nop 2
	ds_read_b128 v[238:241], v166
	ds_read_b128 v[164:167], v167
	s_waitcnt lgkmcnt(0)
	v_mfma_f32_16x16x32_bf16 v[156:159], v[164:167], v[24:27], v[156:159]
	ds_read_b128 v[164:167], v168
	s_waitcnt lgkmcnt(0)
	v_mfma_f32_16x16x32_bf16 v[40:43], v[164:167], v[24:27], v[40:43]
	ds_read_b128 v[164:167], v169
	s_waitcnt lgkmcnt(0)
	v_mfma_f32_16x16x32_bf16 v[36:39], v[164:167], v[24:27], v[36:39]
	ds_read_b128 v[164:167], v170
	s_waitcnt lgkmcnt(0)
	v_mfma_f32_16x16x32_bf16 v[164:167], v[164:167], v[24:27], v[32:35]
	s_nop 2
	ds_read_b128 v[32:35], v171
	v_mfma_f32_16x16x32_bf16 v[238:241], v[238:241], v[24:27], v[242:245]
	s_waitcnt lgkmcnt(0)
	v_mfma_f32_16x16x32_bf16 v[168:171], v[32:35], v[24:27], v[28:31]
	ds_read_b128 v[24:27], v94 offset:128
	s_waitcnt vmcnt(5) lgkmcnt(0)
	v_mfma_f32_16x16x32_bf16 v[44:47], v[24:27], v[20:23], v[44:47]
	ds_read_b128 v[24:27], v94 offset:8576
	s_waitcnt lgkmcnt(0)
	v_mfma_f32_16x16x32_bf16 v[48:51], v[24:27], v[20:23], v[48:51]
	ds_read_b128 v[24:27], v94 offset:17024
	s_waitcnt lgkmcnt(0)
	v_mfma_f32_16x16x32_bf16 v[52:55], v[24:27], v[20:23], v[52:55]
	ds_read_b128 v[24:27], v94 offset:25472
	s_waitcnt lgkmcnt(0)
	v_mfma_f32_16x16x32_bf16 v[56:59], v[24:27], v[20:23], v[56:59]
	ds_read_b128 v[24:27], v94 offset:33920
	s_waitcnt lgkmcnt(0)
	v_mfma_f32_16x16x32_bf16 v[60:63], v[24:27], v[20:23], v[60:63]
	ds_read_b128 v[24:27], v94 offset:42368
	s_waitcnt lgkmcnt(0)
	v_mfma_f32_16x16x32_bf16 v[160:163], v[24:27], v[20:23], v[160:163]
	ds_read_b128 v[24:27], v94 offset:50816
	s_waitcnt lgkmcnt(0)
	v_mfma_f32_16x16x32_bf16 v[222:225], v[24:27], v[20:23], v[222:225]
	ds_read_b128 v[24:27], v94 offset:59264
	s_waitcnt lgkmcnt(0)
	v_mfma_f32_16x16x32_bf16 v[226:229], v[24:27], v[20:23], v[226:229]
	ds_read_b128 v[24:27], v172
	s_waitcnt lgkmcnt(0)
	v_mfma_f32_16x16x32_bf16 v[230:233], v[24:27], v[20:23], v[230:233]
	ds_read_b128 v[24:27], v173
	s_waitcnt lgkmcnt(0)
	v_mfma_f32_16x16x32_bf16 v[234:237], v[24:27], v[20:23], v[234:237]
	ds_read_b128 v[24:27], v174
	s_waitcnt lgkmcnt(0)
	v_mfma_f32_16x16x32_bf16 v[238:241], v[24:27], v[20:23], v[238:241]
	ds_read_b128 v[24:27], v175
	ds_read_b128 v[172:175], v182
	s_waitcnt lgkmcnt(1)
	v_mfma_f32_16x16x32_bf16 v[156:159], v[24:27], v[20:23], v[156:159]
	ds_read_b128 v[24:27], v176
	s_waitcnt lgkmcnt(0)
	v_mfma_f32_16x16x32_bf16 v[32:35], v[24:27], v[20:23], v[40:43]
	ds_read_b128 v[24:27], v177
	s_nop 1
	ds_read_b128 v[40:43], v94 offset:8640
	s_waitcnt lgkmcnt(1)
	v_mfma_f32_16x16x32_bf16 v[28:31], v[24:27], v[20:23], v[36:39]
	ds_read_b128 v[24:27], v178
	s_nop 1
	ds_read_b128 v[36:39], v179
	ds_read_b128 v[176:179], v183
	s_waitcnt lgkmcnt(2)
; #define LAS __attribute__((address_space(3)))
; #define MFMA16(a, b, c) __builtin_amdgcn_mfma_f32_16x16x32_bf16((a), (b), (c), 0, 0, 0)
; __device__ __forceinline__ void xattn_pair(LAS unsigned char* lds, int bh, size_t row_base, bf16* QO, const bf16* Kx, const bf16* VTx, int tid, const WsRef& wsr) {
;     ...
;         for (int kk = 0; kk < 8; ++kk) qf[kk] = *(const bf16x8*)(qp + kk * 32 + fq * 8);
;         f32x4 sx[16];
; #pragma unroll
;         for (int n = 0; n < 16; ++n) sx[n] = (f32x4){0.f, 0.f, 0.f, 0.f};
; #pragma unroll
;         for (int kk = 0; kk < 8; ++kk)
; #pragma unroll
;             for (int n = 0; n < 16; ++n) { const bf16x8 kf = *(const LAS bf16x8*)(T + (n * 16 + fr) * LDX + kk * 32 + fq * 8); sx[n] = MFMA16(kf, qf[kk], sx[n]); }
	v_mfma_f32_16x16x32_bf16 v[24:27], v[24:27], v[20:23], v[164:167]
	s_nop 2
	ds_read_b128 v[164:167], v180
	s_waitcnt lgkmcnt(2)
	v_mfma_f32_16x16x32_bf16 v[20:23], v[36:39], v[20:23], v[168:171]
	ds_read_b128 v[36:39], v94 offset:192
	s_waitcnt vmcnt(4) lgkmcnt(2)
	v_mfma_f32_16x16x32_bf16 v[156:159], v[176:179], v[16:19], v[156:159]
	ds_read_b128 v[176:179], v184
	ds_read_b128 v[168:171], v181
	s_waitcnt lgkmcnt(2)
	v_mfma_f32_16x16x32_bf16 v[36:39], v[36:39], v[16:19], v[44:47]
	s_nop 2
	ds_read_b128 v[44:47], v94 offset:17088
	v_mfma_f32_16x16x32_bf16 v[40:43], v[40:43], v[16:19], v[48:51]
	s_nop 2
	ds_read_b128 v[48:51], v94 offset:25536
	s_waitcnt lgkmcnt(3)
	v_mfma_f32_16x16x32_bf16 v[32:35], v[176:179], v[16:19], v[32:35]
	ds_read_b128 v[176:179], v185
	s_waitcnt lgkmcnt(2)
	v_mfma_f32_16x16x32_bf16 v[44:47], v[44:47], v[16:19], v[52:55]
	s_waitcnt lgkmcnt(1)
	v_mfma_f32_16x16x32_bf16 v[48:51], v[48:51], v[16:19], v[56:59]
	s_nop 0
	ds_read_b128 v[52:55], v94 offset:33984
	s_nop 0
	ds_read_b128 v[56:59], v94 offset:42432
	s_waitcnt lgkmcnt(2)
	v_mfma_f32_16x16x32_bf16 v[176:179], v[176:179], v[16:19], v[28:31]
	s_nop 2
	ds_read_b128 v[28:31], v186
	s_waitcnt lgkmcnt(2)
	v_mfma_f32_16x16x32_bf16 v[52:55], v[52:55], v[16:19], v[60:63]
	s_waitcnt lgkmcnt(1)
	v_mfma_f32_16x16x32_bf16 v[56:59], v[56:59], v[16:19], v[160:163]
	s_nop 0
	ds_read_b128 v[60:63], v94 offset:50880
	s_nop 0
	ds_read_b128 v[160:163], v94 offset:59328
	s_waitcnt lgkmcnt(2)
	v_mfma_f32_16x16x32_bf16 v[180:183], v[28:31], v[16:19], v[24:27]
	s_nop 2
	ds_read_b128 v[24:27], v187
	s_waitcnt lgkmcnt(2)
	v_mfma_f32_16x16x32_bf16 v[60:63], v[60:63], v[16:19], v[222:225]
	s_waitcnt lgkmcnt(1)
	v_mfma_f32_16x16x32_bf16 v[160:163], v[160:163], v[16:19], v[226:229]
	v_mfma_f32_16x16x32_bf16 v[164:167], v[164:167], v[16:19], v[230:233]
	v_mfma_f32_16x16x32_bf16 v[168:171], v[168:171], v[16:19], v[234:237]
	v_mfma_f32_16x16x32_bf16 v[172:175], v[172:175], v[16:19], v[238:241]
	s_waitcnt lgkmcnt(0)
	v_mfma_f32_16x16x32_bf16 v[184:187], v[24:27], v[16:19], v[20:23]
	ds_read_b128 v[16:19], v94 offset:256
	s_waitcnt vmcnt(3) lgkmcnt(0)
	v_mfma_f32_16x16x32_bf16 v[36:39], v[16:19], v[12:15], v[36:39]
	ds_read_b128 v[16:19], v94 offset:8704
	s_waitcnt lgkmcnt(0)
	v_mfma_f32_16x16x32_bf16 v[40:43], v[16:19], v[12:15], v[40:43]
	ds_read_b128 v[16:19], v94 offset:17152
	s_waitcnt lgkmcnt(0)
	v_mfma_f32_16x16x32_bf16 v[44:47], v[16:19], v[12:15], v[44:47]
	ds_read_b128 v[16:19], v94 offset:25600
	s_waitcnt lgkmcnt(0)
	v_mfma_f32_16x16x32_bf16 v[48:51], v[16:19], v[12:15], v[48:51]
	ds_read_b128 v[16:19], v94 offset:34048
	s_waitcnt lgkmcnt(0)
	v_mfma_f32_16x16x32_bf16 v[52:55], v[16:19], v[12:15], v[52:55]
	ds_read_b128 v[16:19], v94 offset:42496
	s_waitcnt lgkmcnt(0)
	v_mfma_f32_16x16x32_bf16 v[56:59], v[16:19], v[12:15], v[56:59]
	ds_read_b128 v[16:19], v94 offset:50944
	s_waitcnt lgkmcnt(0)
	v_mfma_f32_16x16x32_bf16 v[60:63], v[16:19], v[12:15], v[60:63]
	ds_read_b128 v[16:19], v94 offset:59392
	s_waitcnt lgkmcnt(0)
	v_mfma_f32_16x16x32_bf16 v[160:163], v[16:19], v[12:15], v[160:163]
	ds_read_b128 v[16:19], v188
	s_waitcnt lgkmcnt(0)
	v_mfma_f32_16x16x32_bf16 v[164:167], v[16:19], v[12:15], v[164:167]
	ds_read_b128 v[16:19], v189
	s_waitcnt lgkmcnt(0)
	v_mfma_f32_16x16x32_bf16 v[168:171], v[16:19], v[12:15], v[168:171]
	ds_read_b128 v[16:19], v190
	s_waitcnt lgkmcnt(0)
	v_mfma_f32_16x16x32_bf16 v[172:175], v[16:19], v[12:15], v[172:175]
	ds_read_b128 v[16:19], v191
	s_waitcnt lgkmcnt(0)
	v_mfma_f32_16x16x32_bf16 v[28:31], v[16:19], v[12:15], v[156:159]
	ds_read_b128 v[16:19], v192
	s_nop 1
	ds_read_b128 v[156:159], v199
	s_waitcnt lgkmcnt(1)
	v_mfma_f32_16x16x32_bf16 v[24:27], v[16:19], v[12:15], v[32:35]
	ds_read_b128 v[16:19], v193
	s_nop 1
	ds_read_b128 v[32:35], v195
	s_waitcnt lgkmcnt(1)
	v_mfma_f32_16x16x32_bf16 v[20:23], v[16:19], v[12:15], v[176:179]
	ds_read_b128 v[16:19], v194
	s_waitcnt lgkmcnt(0)
	v_mfma_f32_16x16x32_bf16 v[16:19], v[16:19], v[12:15], v[180:183]
	v_mfma_f32_16x16x32_bf16 v[12:15], v[32:35], v[12:15], v[184:187]
	ds_read_b128 v[32:35], v94 offset:320
	s_waitcnt vmcnt(2) lgkmcnt(0)
	v_mfma_f32_16x16x32_bf16 v[32:35], v[32:35], v[8:11], v[36:39]
	s_nop 2
	ds_read_b128 v[36:39], v94 offset:8768
	s_waitcnt lgkmcnt(0)
	v_mfma_f32_16x16x32_bf16 v[36:39], v[36:39], v[8:11], v[40:43]
	s_nop 2
	ds_read_b128 v[40:43], v94 offset:17216
	s_waitcnt lgkmcnt(0)
	v_mfma_f32_16x16x32_bf16 v[40:43], v[40:43], v[8:11], v[44:47]
	s_nop 2
	ds_read_b128 v[44:47], v94 offset:25664
	s_waitcnt lgkmcnt(0)
	v_mfma_f32_16x16x32_bf16 v[44:47], v[44:47], v[8:11], v[48:51]
	s_nop 2
	ds_read_b128 v[48:51], v94 offset:34112
	v_mfma_f32_16x16x32_bf16 v[156:159], v[156:159], v[8:11], v[164:167]
	s_nop 2
	ds_read_b128 v[164:167], v197
	s_waitcnt lgkmcnt(1)
	v_mfma_f32_16x16x32_bf16 v[48:51], v[48:51], v[8:11], v[52:55]
	s_nop 2
	ds_read_b128 v[52:55], v94 offset:42560
	s_waitcnt lgkmcnt(0)
	v_mfma_f32_16x16x32_bf16 v[52:55], v[52:55], v[8:11], v[56:59]
	s_nop 2
	ds_read_b128 v[56:59], v94 offset:51008
	s_waitcnt lgkmcnt(0)
	v_mfma_f32_16x16x32_bf16 v[56:59], v[56:59], v[8:11], v[60:63]
	s_nop 2
	ds_read_b128 v[60:63], v94 offset:59456
	s_waitcnt lgkmcnt(0)
	v_mfma_f32_16x16x32_bf16 v[60:63], v[60:63], v[8:11], v[160:163]
	s_nop 2
	ds_read_b128 v[160:163], v196
	s_waitcnt lgkmcnt(0)
	v_mfma_f32_16x16x32_bf16 v[160:163], v[160:163], v[8:11], v[168:171]
	s_nop 2
	ds_read_b128 v[168:171], v198
	s_waitcnt lgkmcnt(0)
	v_mfma_f32_16x16x32_bf16 v[28:31], v[168:171], v[8:11], v[28:31]
	ds_read_b128 v[168:171], v200
	s_waitcnt lgkmcnt(0)
; #define LAS __attribute__((address_space(3)))
; #define MFMA16(a, b, c) __builtin_amdgcn_mfma_f32_16x16x32_bf16((a), (b), (c), 0, 0, 0)
; __device__ __forceinline__ void xattn_softmax(f32x4 (&s)[16], bf16x8 (&pf)[8], float& rinv) {
;     float mx = -3.0e38f;
; #pragma unroll
;     for (int n = 0; n < 16; ++n) mx = fmaxf(mx, fmaxf(fmaxf(s[n][0], s[n][1]), fmaxf(s[n][2], s[n][3])));
; __device__ __forceinline__ void xattn_pair(LAS unsigned char* lds, int bh, size_t row_base, bf16* QO, const bf16* Kx, const bf16* VTx, int tid, const WsRef& wsr) {
;     ...
;         for (int kk = 0; kk < 8; ++kk)
; #pragma unroll
;             for (int n = 0; n < 16; ++n) { const bf16x8 kf = *(const LAS bf16x8*)(T + (n * 16 + fr) * LDX + kk * 32 + fq * 8); sx[n] = MFMA16(kf, qf[kk], sx[n]); }
	v_mfma_f32_16x16x32_bf16 v[24:27], v[168:171], v[8:11], v[24:27]
	ds_read_b128 v[168:171], v201
	s_waitcnt lgkmcnt(0)
	v_mfma_f32_16x16x32_bf16 v[20:23], v[168:171], v[8:11], v[20:23]
	ds_read_b128 v[168:171], v202
	s_waitcnt lgkmcnt(0)
	v_mfma_f32_16x16x32_bf16 v[16:19], v[168:171], v[8:11], v[16:19]
	ds_read_b128 v[168:171], v203
	v_mfma_f32_16x16x32_bf16 v[164:167], v[164:167], v[8:11], v[172:175]
	s_waitcnt lgkmcnt(0)
	v_mfma_f32_16x16x32_bf16 v[8:11], v[168:171], v[8:11], v[12:15]
	s_nop 2
	ds_read_b128 v[12:15], v94 offset:384
	s_waitcnt vmcnt(1) lgkmcnt(0)
	v_mfma_f32_16x16x32_bf16 v[12:15], v[12:15], v[4:7], v[32:35]
	s_nop 2
	ds_read_b128 v[32:35], v94 offset:8832
	s_waitcnt lgkmcnt(0)
	v_mfma_f32_16x16x32_bf16 v[32:35], v[32:35], v[4:7], v[36:39]
	s_nop 2
	ds_read_b128 v[36:39], v94 offset:17280
	s_waitcnt lgkmcnt(0)
	v_mfma_f32_16x16x32_bf16 v[36:39], v[36:39], v[4:7], v[40:43]
	s_nop 2
	ds_read_b128 v[40:43], v94 offset:25728
	s_waitcnt lgkmcnt(0)
	v_mfma_f32_16x16x32_bf16 v[40:43], v[40:43], v[4:7], v[44:47]
	s_nop 2
	ds_read_b128 v[44:47], v94 offset:34176
	s_waitcnt lgkmcnt(0)
	v_mfma_f32_16x16x32_bf16 v[44:47], v[44:47], v[4:7], v[48:51]
	s_nop 2
	ds_read_b128 v[48:51], v94 offset:42624
	s_waitcnt lgkmcnt(0)
	v_mfma_f32_16x16x32_bf16 v[168:171], v[48:51], v[4:7], v[52:55]
	ds_read_b128 v[48:51], v94 offset:51072
	s_waitcnt lgkmcnt(0)
	v_mfma_f32_16x16x32_bf16 v[172:175], v[48:51], v[4:7], v[56:59]
	ds_read_b128 v[48:51], v94 offset:59520
	s_waitcnt lgkmcnt(0)
	v_mfma_f32_16x16x32_bf16 v[176:179], v[48:51], v[4:7], v[60:63]
	ds_read_b128 v[48:51], v209
	s_waitcnt lgkmcnt(0)
	v_mfma_f32_16x16x32_bf16 v[156:159], v[48:51], v[4:7], v[156:159]
	ds_read_b128 v[48:51], v211
	s_waitcnt lgkmcnt(0)
	v_mfma_f32_16x16x32_bf16 v[160:163], v[48:51], v[4:7], v[160:163]
	ds_read_b128 v[48:51], v215
	s_waitcnt lgkmcnt(0)
	v_mfma_f32_16x16x32_bf16 v[164:167], v[48:51], v[4:7], v[164:167]
	ds_read_b128 v[48:51], v216
	s_waitcnt lgkmcnt(0)
	v_mfma_f32_16x16x32_bf16 v[180:183], v[48:51], v[4:7], v[28:31]
	s_nop 2
	ds_read_b128 v[28:31], v217
	s_waitcnt lgkmcnt(0)
	v_mfma_f32_16x16x32_bf16 v[184:187], v[28:31], v[4:7], v[24:27]
	s_nop 2
	ds_read_b128 v[24:27], v218
	s_waitcnt lgkmcnt(0)
	v_mfma_f32_16x16x32_bf16 v[188:191], v[24:27], v[4:7], v[20:23]
	s_nop 2
	ds_read_b128 v[20:23], v219
	s_waitcnt lgkmcnt(0)
	v_mfma_f32_16x16x32_bf16 v[192:195], v[20:23], v[4:7], v[16:19]
	s_nop 2
	ds_read_b128 v[16:19], v220
	s_waitcnt lgkmcnt(0)
	v_mfma_f32_16x16x32_bf16 v[196:199], v[16:19], v[4:7], v[8:11]
	ds_read_b128 v[4:7], v94 offset:448
	s_waitcnt vmcnt(0) lgkmcnt(0)
	v_mfma_f32_16x16x32_bf16 v[60:63], v[4:7], v[0:3], v[12:15]
	ds_read_b128 v[4:7], v94 offset:8896
	s_nop 6
	v_max_f32_e32 v86, v63, v63
	s_waitcnt lgkmcnt(0)
	v_mfma_f32_16x16x32_bf16 v[56:59], v[4:7], v[0:3], v[32:35]
	ds_read_b128 v[4:7], v94 offset:17344
	v_max_f32_e32 v87, v62, v62
	v_max_f32_e32 v86, v87, v86
	s_waitcnt lgkmcnt(0)
	v_mfma_f32_16x16x32_bf16 v[52:55], v[4:7], v[0:3], v[36:39]
	ds_read_b128 v[4:7], v94 offset:25792
	s_nop 1
	v_max_f32_e32 v87, v59, v59
	v_max3_f32 v86, v60, v61, v86
	s_waitcnt lgkmcnt(0)
	v_mfma_f32_16x16x32_bf16 v[48:51], v[4:7], v[0:3], v[40:43]
	ds_read_b128 v[4:7], v94 offset:34240
	s_nop 6
	v_max_f32_e32 v99, v50, v50
	s_waitcnt lgkmcnt(0)
	v_mfma_f32_16x16x32_bf16 v[44:47], v[4:7], v[0:3], v[44:47]
	ds_read_b128 v[4:7], v94 offset:42688
	s_waitcnt lgkmcnt(0)
	v_mfma_f32_16x16x32_bf16 v[40:43], v[4:7], v[0:3], v[168:171]
	ds_read_b128 v[4:7], v94 offset:51136
	s_waitcnt lgkmcnt(0)
	v_mfma_f32_16x16x32_bf16 v[36:39], v[4:7], v[0:3], v[172:175]
	ds_read_b128 v[4:7], v94 offset:59584
	v_max_f32_e32 v94, v58, v58
	v_max_f32_e32 v87, v94, v87
	s_waitcnt lgkmcnt(0)
	v_mfma_f32_16x16x32_bf16 v[32:35], v[4:7], v[0:3], v[176:179]
	ds_read_b128 v[4:7], v205
	v_max3_f32 v87, v56, v57, v87
	v_max3_f32 v86, v86, s8, v87
	s_waitcnt lgkmcnt(0)
	v_mfma_f32_16x16x32_bf16 v[28:31], v[4:7], v[0:3], v[156:159]
	ds_read_b128 v[4:7], v206
	s_nop 1
	ds_read_b128 v[156:159], v214
	v_max_f32_e32 v87, v55, v55
	s_waitcnt lgkmcnt(1)
	v_mfma_f32_16x16x32_bf16 v[24:27], v[4:7], v[0:3], v[160:163]
	ds_read_b128 v[4:7], v207
	v_max_f32_e32 v94, v54, v54
	v_max_f32_e32 v87, v94, v87
	s_waitcnt lgkmcnt(0)
	v_mfma_f32_16x16x32_bf16 v[20:23], v[4:7], v[0:3], v[164:167]
	ds_read_b128 v[4:7], v208
	v_max_f32_e32 v94, v51, v51
	v_max_f32_e32 v94, v99, v94
	s_waitcnt lgkmcnt(0)
	v_mfma_f32_16x16x32_bf16 v[16:19], v[4:7], v[0:3], v[180:183]
	ds_read_b128 v[4:7], v210
	v_max3_f32 v87, v52, v53, v87
	v_max3_f32 v94, v48, v49, v94
	s_waitcnt lgkmcnt(0)
	v_mfma_f32_16x16x32_bf16 v[12:15], v[4:7], v[0:3], v[184:187]
	ds_read_b128 v[4:7], v212
	v_max3_f32 v86, v86, v87, v94
	v_max_f32_e32 v87, v47, v47
	v_max_f32_e32 v94, v46, v46
	v_max_f32_e32 v87, v94, v87
	v_max_f32_e32 v94, v43, v43
	v_max_f32_e32 v99, v42, v42
	v_max_f32_e32 v94, v99, v94
	v_max3_f32 v87, v44, v45, v87
	v_max3_f32 v94, v40, v41, v94
	v_max3_f32 v86, v86, v87, v94
	v_max_f32_e32 v87, v39, v39
	v_max_f32_e32 v94, v38, v38
	v_max_f32_e32 v87, v94, v87
	v_max_f32_e32 v94, v35, v35
	v_max_f32_e32 v99, v34, v34
	v_max_f32_e32 v94, v99, v94
	s_waitcnt lgkmcnt(0)
	v_mfma_f32_16x16x32_bf16 v[8:11], v[4:7], v[0:3], v[188:191]
	ds_read_b128 v[4:7], v213
	v_max3_f32 v87, v36, v37, v87
	v_max3_f32 v94, v32, v33, v94
	v_max3_f32 v86, v86, v87, v94
	v_max_f32_e32 v87, v31, v31
	v_max_f32_e32 v94, v30, v30
	v_max_f32_e32 v87, v94, v87
	v_max_f32_e32 v94, v27, v27
	v_max_f32_e32 v99, v26, v26
	v_max_f32_e32 v94, v99, v94
	v_max3_f32 v87, v28, v29, v87
	v_max3_f32 v94, v24, v25, v94
	v_max3_f32 v86, v86, v87, v94
	v_max_f32_e32 v87, v23, v23
	v_max_f32_e32 v94, v22, v22
	v_max_f32_e32 v87, v94, v87
	v_max_f32_e32 v94, v19, v19
	v_max_f32_e32 v99, v18, v18
	v_max_f32_e32 v94, v99, v94
	v_max3_f32 v87, v20, v21, v87
	v_max3_f32 v94, v16, v17, v94
	s_waitcnt lgkmcnt(0)
; __device__ __forceinline__ float fexp2(float x) { return __builtin_amdgcn_exp2f(x); }
; __device__ __forceinline__ void xattn_softmax(f32x4 (&s)[16], bf16x8 (&pf)[8], float& rinv) {
;     ...
;     for (int n = 0; n < 16; ++n) mx = fmaxf(mx, fmaxf(fmaxf(s[n][0], s[n][1]), fmaxf(s[n][2], s[n][3])));
;     mx = fmaxf(mx, __shfl_xor(mx, 16)); mx = fmaxf(mx, __shfl_xor(mx, 32));
;     const float sc = 0.0625f * LOG2E; float sum = 0.f;
; #pragma unroll
;     for (int n = 0; n < 16; ++n)
; #pragma unroll
;         for (int r = 0; r < 4; ++r) { const float p = fexp2((s[n][r] - mx) * sc); s[n][r] = p; sum += p; }
	v_mfma_f32_16x16x32_bf16 v[4:7], v[4:7], v[0:3], v[192:195]
	v_max3_f32 v86, v86, v87, v94
	v_max_f32_e32 v87, v15, v15
	v_max_f32_e32 v94, v14, v14
	v_mfma_f32_16x16x32_bf16 v[0:3], v[156:159], v[0:3], v[196:199]
	v_max_f32_e32 v87, v94, v87
	v_max_f32_e32 v94, v11, v11
	v_max_f32_e32 v99, v10, v10
	v_max_f32_e32 v94, v99, v94
	v_max3_f32 v87, v12, v13, v87
	v_max3_f32 v94, v8, v9, v94
	v_max3_f32 v86, v86, v87, v94
	v_max_f32_e32 v87, v7, v7
	v_max_f32_e32 v94, v6, v6
	v_max_f32_e32 v87, v94, v87
	v_max_f32_e32 v94, v3, v3
	v_max_f32_e32 v99, v2, v2
	v_max_f32_e32 v94, v99, v94
	v_max3_f32 v87, v4, v5, v87
	v_max3_f32 v94, v0, v1, v94
	v_max3_f32 v86, v86, v87, v94
	ds_bpermute_b32 v87, v155, v86
	s_waitcnt lgkmcnt(0)
	v_max_f32_e32 v87, v87, v87
	v_max_f32_e32 v86, v86, v87
	ds_bpermute_b32 v87, v64, v86
	s_waitcnt lgkmcnt(0)
	v_max_f32_e32 v87, v87, v87
	v_max_f32_e32 v99, v86, v87
	v_sub_f32_e32 v61, v61, v99
	v_sub_f32_e32 v60, v60, v99
	v_mul_f32_e32 v61, 0x3db8aa3b, v61
	v_mul_f32_e32 v60, 0x3db8aa3b, v60
	v_exp_f32_e32 v168, v61
	v_sub_f32_e32 v61, v62, v99
	v_exp_f32_e32 v165, v60
	v_mul_f32_e32 v61, 0x3db8aa3b, v61
	v_exp_f32_e32 v167, v61
	v_sub_f32_e32 v61, v63, v99
	v_sub_f32_e32 v57, v57, v99
	v_mul_f32_e32 v61, 0x3db8aa3b, v61
	v_sub_f32_e32 v56, v56, v99
	v_mul_f32_e32 v57, 0x3db8aa3b, v57
	v_exp_f32_e32 v170, v61
	v_mul_f32_e32 v56, 0x3db8aa3b, v56
	v_exp_f32_e32 v174, v57
	v_sub_f32_e32 v57, v58, v99
	v_add_f32_e32 v60, 0, v165
	v_exp_f32_e32 v173, v56
	v_mul_f32_e32 v57, 0x3db8aa3b, v57
	v_add_f32_e32 v60, v168, v60
	v_exp_f32_e32 v175, v57
	v_sub_f32_e32 v57, v59, v99
	v_sub_f32_e32 v53, v53, v99
	v_add_f32_e32 v60, v167, v60
	v_mul_f32_e32 v57, 0x3db8aa3b, v57
	v_sub_f32_e32 v52, v52, v99
	v_mul_f32_e32 v53, 0x3db8aa3b, v53
	v_add_f32_e32 v60, v170, v60
	v_exp_f32_e32 v176, v57
	v_mul_f32_e32 v52, 0x3db8aa3b, v52
	v_exp_f32_e32 v160, v53
	v_sub_f32_e32 v53, v54, v99
	v_add_f32_e32 v56, v173, v60
	v_exp_f32_e32 v62, v52
	v_mul_f32_e32 v53, 0x3db8aa3b, v53
	v_add_f32_e32 v56, v174, v56
	v_exp_f32_e32 v54, v53
	v_sub_f32_e32 v53, v55, v99
	v_sub_f32_e32 v49, v49, v99
	v_add_f32_e32 v56, v175, v56
	v_mul_f32_e32 v53, 0x3db8aa3b, v53
	v_sub_f32_e32 v48, v48, v99
	v_mul_f32_e32 v49, 0x3db8aa3b, v49
	v_add_f32_e32 v56, v176, v56
	v_exp_f32_e32 v161, v53
	v_mul_f32_e32 v48, 0x3db8aa3b, v48
	v_exp_f32_e32 v169, v49
	v_sub_f32_e32 v49, v50, v99
	v_add_f32_e32 v52, v62, v56
	v_exp_f32_e32 v166, v48
	v_mul_f32_e32 v49, 0x3db8aa3b, v49
	v_add_f32_e32 v52, v160, v52
	v_exp_f32_e32 v171, v49
	v_sub_f32_e32 v49, v51, v99
	v_add_f32_e32 v52, v54, v52
	v_mul_f32_e32 v49, 0x3db8aa3b, v49
	v_sub_f32_e32 v44, v44, v99
	v_add_f32_e32 v52, v161, v52
	v_exp_f32_e32 v172, v49
	v_mul_f32_e32 v44, 0x3db8aa3b, v44
	v_sub_f32_e32 v45, v45, v99
	v_add_f32_e32 v48, v166, v52
	v_exp_f32_e32 v44, v44
	v_mul_f32_e32 v45, 0x3db8aa3b, v45
	v_sub_f32_e32 v46, v46, v99
	v_add_f32_e32 v48, v169, v48
	v_exp_f32_e32 v45, v45
	v_mul_f32_e32 v46, 0x3db8aa3b, v46
	v_sub_f32_e32 v47, v47, v99
	v_sub_f32_e32 v41, v41, v99
	v_add_f32_e32 v48, v171, v48
	v_exp_f32_e32 v52, v46
	v_mul_f32_e32 v47, 0x3db8aa3b, v47
	v_sub_f32_e32 v40, v40, v99
	v_mul_f32_e32 v41, 0x3db8aa3b, v41
	v_add_f32_e32 v48, v172, v48
	v_exp_f32_e32 v53, v47
	v_mul_f32_e32 v40, 0x3db8aa3b, v40
	v_exp_f32_e32 v163, v41
	v_sub_f32_e32 v41, v42, v99
	v_add_f32_e32 v48, v44, v48
	v_exp_f32_e32 v55, v40
	v_mul_f32_e32 v41, 0x3db8aa3b, v41
	v_add_f32_e32 v48, v45, v48
	v_exp_f32_e32 v164, v41
	v_sub_f32_e32 v41, v43, v99
	v_sub_f32_e32 v37, v37, v99
	v_add_f32_e32 v46, v52, v48
	v_mul_f32_e32 v41, 0x3db8aa3b, v41
	v_sub_f32_e32 v36, v36, v99
	v_mul_f32_e32 v37, 0x3db8aa3b, v37
	v_add_f32_e32 v46, v53, v46
	v_exp_f32_e32 v43, v41
	v_mul_f32_e32 v36, 0x3db8aa3b, v36
	v_exp_f32_e32 v50, v37
	v_sub_f32_e32 v37, v38, v99
	v_add_f32_e32 v40, v55, v46
	v_exp_f32_e32 v48, v36
	v_mul_f32_e32 v37, 0x3db8aa3b, v37
	v_add_f32_e32 v40, v163, v40
	v_exp_f32_e32 v49, v37
	v_sub_f32_e32 v37, v39, v99
	v_sub_f32_e32 v33, v33, v99
	v_add_f32_e32 v40, v164, v40
	v_mul_f32_e32 v37, 0x3db8aa3b, v37
	v_sub_f32_e32 v32, v32, v99
	v_mul_f32_e32 v33, 0x3db8aa3b, v33
	v_add_f32_e32 v40, v43, v40
	v_exp_f32_e32 v51, v37
	v_mul_f32_e32 v32, 0x3db8aa3b, v32
	v_exp_f32_e32 v61, v33
	v_sub_f32_e32 v33, v34, v99
	v_add_f32_e32 v36, v48, v40
	v_exp_f32_e32 v60, v32
	v_mul_f32_e32 v33, 0x3db8aa3b, v33
	v_add_f32_e32 v36, v50, v36
	v_exp_f32_e32 v63, v33
	v_sub_f32_e32 v33, v35, v99
	v_sub_f32_e32 v29, v29, v99
	v_add_f32_e32 v36, v49, v36
	v_mul_f32_e32 v33, 0x3db8aa3b, v33
	v_sub_f32_e32 v28, v28, v99
	v_mul_f32_e32 v29, 0x3db8aa3b, v29
	v_add_f32_e32 v36, v51, v36
	v_exp_f32_e32 v162, v33
	v_mul_f32_e32 v28, 0x3db8aa3b, v28
	v_exp_f32_e32 v58, v29
	v_sub_f32_e32 v29, v30, v99
	v_add_f32_e32 v32, v60, v36
	v_exp_f32_e32 v56, v28
	v_mul_f32_e32 v29, 0x3db8aa3b, v29
	v_add_f32_e32 v32, v61, v32
	v_exp_f32_e32 v57, v29
	v_sub_f32_e32 v29, v31, v99
	v_sub_f32_e32 v25, v25, v99
	v_add_f32_e32 v32, v63, v32
	v_mul_f32_e32 v29, 0x3db8aa3b, v29
	v_sub_f32_e32 v24, v24, v99
	v_mul_f32_e32 v25, 0x3db8aa3b, v25
	v_add_f32_e32 v32, v162, v32
	v_exp_f32_e32 v59, v29
	v_mul_f32_e32 v24, 0x3db8aa3b, v24
	v_exp_f32_e32 v157, v25
	v_sub_f32_e32 v25, v26, v99
	v_add_f32_e32 v28, v56, v32
	v_exp_f32_e32 v156, v24
	v_mul_f32_e32 v25, 0x3db8aa3b, v25
	v_add_f32_e32 v28, v58, v28
	v_exp_f32_e32 v158, v25
	v_sub_f32_e32 v25, v27, v99
	v_sub_f32_e32 v21, v21, v99
	v_add_f32_e32 v28, v57, v28
	v_mul_f32_e32 v25, 0x3db8aa3b, v25
	v_sub_f32_e32 v20, v20, v99
	v_mul_f32_e32 v21, 0x3db8aa3b, v21
	v_add_f32_e32 v28, v59, v28
	v_exp_f32_e32 v159, v25
; #define LAS __attribute__((address_space(3)))
; __device__ __forceinline__ float fexp2(float x) { return __builtin_amdgcn_exp2f(x); }
; __device__ __forceinline__ void xattn_softmax(f32x4 (&s)[16], bf16x8 (&pf)[8], float& rinv) {
;     ...
;     for (int n = 0; n < 16; ++n)
; #pragma unroll
;         for (int r = 0; r < 4; ++r) { const float p = fexp2((s[n][r] - mx) * sc); s[n][r] = p; sum += p; }
;     sum += __shfl_xor(sum, 16); sum += __shfl_xor(sum, 32);
;     rinv = 1.f / sum;
; __device__ __forceinline__ void xattn_pair(LAS unsigned char* lds, int bh, size_t row_base, bf16* QO, const bf16* Kx, const bf16* VTx, int tid, const WsRef& wsr) {
;     ...
;     __syncthreads();
;     const u32x4* vg = (const u32x4*)(VTx + (size_t)bh * 65536);
; #pragma unroll 4
;     for (int i = 0; i < 16; ++i) { const int id = tid + 512 * i, r = id >> 5, ch = id & 31; *(LAS u32x4*)(T + r * LDX + ch * 8) = vg[id]; }
;     __syncthreads();
	v_mul_f32_e32 v20, 0x3db8aa3b, v20
	v_exp_f32_e32 v38, v21
	v_sub_f32_e32 v21, v22, v99
	v_add_f32_e32 v24, v156, v28
	v_exp_f32_e32 v36, v20
	v_mul_f32_e32 v21, 0x3db8aa3b, v21
	v_add_f32_e32 v24, v157, v24
	v_exp_f32_e32 v37, v21
	v_sub_f32_e32 v21, v23, v99
	v_sub_f32_e32 v17, v17, v99
	v_add_f32_e32 v24, v158, v24
	v_mul_f32_e32 v21, 0x3db8aa3b, v21
	v_sub_f32_e32 v16, v16, v99
	v_mul_f32_e32 v17, 0x3db8aa3b, v17
	v_add_f32_e32 v24, v159, v24
	v_exp_f32_e32 v39, v21
	v_mul_f32_e32 v16, 0x3db8aa3b, v16
	v_exp_f32_e32 v87, v17
	v_sub_f32_e32 v17, v18, v99
	v_add_f32_e32 v20, v36, v24
	v_exp_f32_e32 v86, v16
	v_mul_f32_e32 v17, 0x3db8aa3b, v17
	v_add_f32_e32 v20, v38, v20
	v_exp_f32_e32 v94, v17
	v_sub_f32_e32 v17, v19, v99
	v_add_f32_e32 v20, v37, v20
	v_mul_f32_e32 v17, 0x3db8aa3b, v17
	v_sub_f32_e32 v12, v12, v99
	v_add_f32_e32 v20, v39, v20
	v_exp_f32_e32 v19, v17
	v_mul_f32_e32 v12, 0x3db8aa3b, v12
	v_sub_f32_e32 v13, v13, v99
	v_add_f32_e32 v16, v86, v20
	v_exp_f32_e32 v12, v12
	v_mul_f32_e32 v13, 0x3db8aa3b, v13
	v_sub_f32_e32 v14, v14, v99
	v_add_f32_e32 v16, v87, v16
	v_exp_f32_e32 v13, v13
	v_mul_f32_e32 v14, 0x3db8aa3b, v14
	v_sub_f32_e32 v15, v15, v99
	v_add_f32_e32 v16, v94, v16
	v_exp_f32_e32 v14, v14
	v_mul_f32_e32 v15, 0x3db8aa3b, v15
	v_add_f32_e32 v16, v19, v16
	v_exp_f32_e32 v15, v15
	v_add_f32_e32 v16, v12, v16
	v_add_f32_e32 v16, v13, v16
	v_sub_f32_e32 v8, v8, v99
	v_add_f32_e32 v16, v14, v16
	v_mul_f32_e32 v8, 0x3db8aa3b, v8
	v_add_f32_e32 v17, v15, v16
	v_exp_f32_e32 v16, v8
	v_sub_f32_e32 v9, v9, v99
	v_mul_f32_e32 v9, 0x3db8aa3b, v9
	v_sub_f32_e32 v4, v4, v99
	v_add_f32_e32 v8, v16, v17
	v_exp_f32_e32 v17, v9
	v_mul_f32_e32 v4, 0x3db8aa3b, v4
	v_sub_f32_e32 v5, v5, v99
	v_exp_f32_e32 v4, v4
	v_add_f32_e32 v9, v17, v8
	v_sub_f32_e32 v8, v10, v99
	v_mul_f32_e32 v8, 0x3db8aa3b, v8
	v_exp_f32_e32 v8, v8
	v_mul_f32_e32 v5, 0x3db8aa3b, v5
	v_sub_f32_e32 v6, v6, v99
	v_exp_f32_e32 v5, v5
	v_add_f32_e32 v10, v8, v9
	v_sub_f32_e32 v9, v11, v99
	v_mul_f32_e32 v9, 0x3db8aa3b, v9
	v_exp_f32_e32 v9, v9
	v_mul_f32_e32 v6, 0x3db8aa3b, v6
	v_sub_f32_e32 v7, v7, v99
	v_exp_f32_e32 v6, v6
	v_mul_f32_e32 v7, 0x3db8aa3b, v7
	v_add_f32_e32 v10, v9, v10
	v_exp_f32_e32 v7, v7
	v_add_f32_e32 v10, v4, v10
	v_add_f32_e32 v10, v5, v10
	v_sub_f32_e32 v0, v0, v99
	v_add_f32_e32 v10, v6, v10
	v_mul_f32_e32 v0, 0x3db8aa3b, v0
	v_add_f32_e32 v11, v7, v10
	v_exp_f32_e32 v10, v0
	v_sub_f32_e32 v1, v1, v99
	v_mul_f32_e32 v1, 0x3db8aa3b, v1
	v_exp_f32_e32 v18, v1
	v_sub_f32_e32 v1, v2, v99
	v_mul_f32_e32 v1, 0x3db8aa3b, v1
	v_add_f32_e32 v0, v10, v11
	v_exp_f32_e32 v11, v1
	v_sub_f32_e32 v1, v3, v99
	v_mul_f32_e32 v1, 0x3db8aa3b, v1
	v_exp_f32_e32 v3, v1
	v_add_f32_e32 v0, v18, v0
	v_add_f32_e32 v0, v11, v0
	v_add_f32_e32 v0, v3, v0
	ds_bpermute_b32 v1, v155, v0
	v_lshrrev_b32_e32 v2, 5, v93
	v_mul_u32_u24_e32 v2, 0x210, v2
	v_add3_u32 v2, v2, v92, 0
	s_mov_b64 s[8:9], 0
	s_waitcnt lgkmcnt(0)
	s_barrier
.LBB0_706:
	s_mov_b32 s9, 0
	s_mov_b32 s8, 0x2300000
	v_lshl_add_u64 v[40:41], v[84:85], 0, s[8:9]
	global_load_dwordx4 v[20:23], v[40:41], off
	s_mov_b32 s8, 0x2302000
	v_lshl_add_u64 v[40:41], v[84:85], 0, s[8:9]
	global_load_dwordx4 v[24:27], v[40:41], off
	s_mov_b32 s8, 0x2304000
	v_lshl_add_u64 v[40:41], v[84:85], 0, s[8:9]
	global_load_dwordx4 v[28:31], v[40:41], off
	s_mov_b32 s8, 0x2306000
	v_lshl_add_u64 v[40:41], v[84:85], 0, s[8:9]
	global_load_dwordx4 v[32:35], v[40:41], off
	s_mov_b32 s8, 0x2308000
	v_lshl_add_u64 v[40:41], v[84:85], 0, s[8:9]
	global_load_dwordx4 v[180:183], v[40:41], off
	s_mov_b32 s8, 0x230a000
	v_lshl_add_u64 v[40:41], v[84:85], 0, s[8:9]
	global_load_dwordx4 v[184:187], v[40:41], off
	s_mov_b32 s8, 0x230c000
	v_lshl_add_u64 v[40:41], v[84:85], 0, s[8:9]
	global_load_dwordx4 v[188:191], v[40:41], off
	s_mov_b32 s8, 0x230e000
	v_lshl_add_u64 v[40:41], v[84:85], 0, s[8:9]
	global_load_dwordx4 v[192:195], v[40:41], off
	s_mov_b32 s8, 0x2310000
	v_lshl_add_u64 v[40:41], v[84:85], 0, s[8:9]
	global_load_dwordx4 v[196:199], v[40:41], off
	s_mov_b32 s8, 0x2312000
	v_lshl_add_u64 v[40:41], v[84:85], 0, s[8:9]
	global_load_dwordx4 v[200:203], v[40:41], off
	s_mov_b32 s8, 0x2314000
	v_lshl_add_u64 v[40:41], v[84:85], 0, s[8:9]
	global_load_dwordx4 v[208:211], v[40:41], off
	s_mov_b32 s8, 0x2316000
	v_lshl_add_u64 v[40:41], v[84:85], 0, s[8:9]
	global_load_dwordx4 v[212:215], v[40:41], off
	s_mov_b32 s8, 0x2318000
	v_lshl_add_u64 v[40:41], v[84:85], 0, s[8:9]
	global_load_dwordx4 v[216:219], v[40:41], off
	s_mov_b32 s8, 0x231a000
	v_lshl_add_u64 v[40:41], v[84:85], 0, s[8:9]
	global_load_dwordx4 v[220:223], v[40:41], off
	s_mov_b32 s8, 0x231c000
	v_lshl_add_u64 v[40:41], v[84:85], 0, s[8:9]
	global_load_dwordx4 v[224:227], v[40:41], off
	s_mov_b32 s8, 0x231e000
	v_lshl_add_u64 v[40:41], v[84:85], 0, s[8:9]
	global_load_dwordx4 v[228:231], v[40:41], off
	s_waitcnt vmcnt(15)
	ds_write_b128 v91, v[20:23]
	s_waitcnt vmcnt(14)
	ds_write_b128 v90, v[24:27]
	s_waitcnt vmcnt(13)
	ds_write_b128 v2, v[28:31]
	s_waitcnt vmcnt(12)
	ds_write_b128 v89, v[32:35]
	s_waitcnt vmcnt(11)
	ds_write_b128 v91, v[180:183] offset:33792
	s_waitcnt vmcnt(10)
	ds_write_b128 v90, v[184:187] offset:33792
	s_waitcnt vmcnt(9)
	ds_write_b128 v2, v[188:191] offset:33792
	s_waitcnt vmcnt(8)
	ds_write_b128 v89, v[192:195] offset:33792
	v_add_u32_e32 v91, 0x10800, v91
	v_add_u32_e32 v90, 0x10800, v90
	v_add_u32_e32 v2, 0x10800, v2
	v_add_u32_e32 v89, 0x10800, v89
	s_waitcnt vmcnt(7)
	ds_write_b128 v91, v[196:199]
	s_waitcnt vmcnt(6)
	ds_write_b128 v90, v[200:203]
	s_waitcnt vmcnt(5)
	ds_write_b128 v2, v[208:211]
	s_waitcnt vmcnt(4)
	ds_write_b128 v89, v[212:215]
	s_waitcnt vmcnt(3)
	ds_write_b128 v91, v[216:219] offset:33792
	s_waitcnt vmcnt(2)
	ds_write_b128 v90, v[220:223] offset:33792
	s_waitcnt vmcnt(1)
	ds_write_b128 v2, v[224:227] offset:33792
	s_waitcnt vmcnt(0)
	ds_write_b128 v89, v[228:231] offset:33792
	v_add_u32_e32 v99, 0, v109
	v_add_u32_e32 v155, v99, v88
	s_waitcnt lgkmcnt(0)
	s_barrier
; #define LAS __attribute__((address_space(3)))
; __device__ __forceinline__ unsigned pk2(float lo, float hi) { return pg8::cvt_pk_bf16(lo, hi); }
; #define MFMA16(a, b, c) __builtin_amdgcn_mfma_f32_16x16x32_bf16((a), (b), (c), 0, 0, 0)
; __device__ __forceinline__ void xattn_softmax(f32x4 (&s)[16], bf16x8 (&pf)[8], float& rinv) {
;     ...
; #pragma unroll
;     for (int kk = 0; kk < 8; ++kk) { u32x4 w; w.x = pk2(s[2 * kk][0], s[2 * kk][1]); w.y = pk2(s[2 * kk][2], s[2 * kk][3]); w.z = pk2(s[2 * kk + 1][0], s[2 * kk + 1][1]); w.w = pk2(s[2 * kk + 1][2], s[2 * kk + 1][3]);
;         pf[kk] = __builtin_bit_cast(bf16x8, w); }
; __device__ __forceinline__ void xattn_pair(LAS unsigned char* lds, int bh, size_t row_base, bf16* QO, const bf16* Kx, const bf16* VTx, int tid, const WsRef& wsr) {
;     ...
;     for (int nh = 0; nh < 2; ++nh) {
;         f32x4 o0[8], o1[8];
; #pragma unroll
;         for (int n = 0; n < 8; ++n) { o0[n] = (f32x4){0.f, 0.f, 0.f, 0.f}; o1[n] = (f32x4){0.f, 0.f, 0.f, 0.f}; }
; #pragma unroll
;         for (int kk = 0; kk < 8; ++kk)
; #pragma unroll
;             for (int n = 0; n < 8; ++n) { const LAS bf16* vp = T + ((nh * 8 + n) * 16 + fr) * LDX + kk * 32 + 4 * fq;
;                 const u32x2 lo = *(const LAS u32x2*)vp, hi = *(const LAS u32x2*)(vp + 16); u32x4 w; w.x = lo.x; w.y = lo.y; w.z = hi.x; w.w = hi.y; const bf16x8 vf = __builtin_bit_cast(bf16x8, w);
;                 o0[n] = MFMA16(vf, pf0[kk], o0[n]); o1[n] = MFMA16(vf, pf1[kk], o1[n]); }
	ds_read2_b64 v[28:31], v155 offset1:4
	v_cvt_pk_bf16_f32 v20, v165, v168
	v_cvt_pk_bf16_f32 v24, v133, v136
	v_cvt_pk_bf16_f32 v25, v140, v144
	v_cvt_pk_bf16_f32 v26, v149, v150
	v_cvt_pk_bf16_f32 v27, v151, v152
	v_cvt_pk_bf16_f32 v21, v167, v170
	v_cvt_pk_bf16_f32 v22, v173, v174
	v_cvt_pk_bf16_f32 v23, v175, v176
	v_add_u32_e32 v133, 0x2000, v155
	s_waitcnt lgkmcnt(0)
	v_mfma_f32_16x16x32_bf16 v[88:91], v[28:31], v[24:27], 0
	v_add_u32_e32 v136, 0x4000, v155
	v_add_u32_e32 v140, 0x6000, v155
	v_add_u32_e32 v144, 0x8000, v155
	v_mfma_f32_16x16x32_bf16 v[174:177], v[28:31], v[20:23], 0
	ds_read2_b64 v[28:31], v133 offset0:32 offset1:36
	v_add_u32_e32 v149, 0xa000, v155
	v_add_u32_e32 v150, 0xc000, v155
	s_waitcnt lgkmcnt(0)
	v_mfma_f32_16x16x32_bf16 v[178:181], v[28:31], v[24:27], 0
	ds_read2_b64 v[238:241], v155 offset0:8 offset1:12
	v_cvt_pk_bf16_f32 v32, v118, v123
	v_cvt_pk_bf16_f32 v33, v127, v132
	v_mfma_f32_16x16x32_bf16 v[182:185], v[28:31], v[20:23], 0
	ds_read2_b64 v[28:31], v136 offset0:64 offset1:68
	v_cvt_pk_bf16_f32 v34, v139, v143
	v_cvt_pk_bf16_f32 v35, v146, v148
	s_waitcnt lgkmcnt(0)
	v_mfma_f32_16x16x32_bf16 v[186:189], v[28:31], v[24:27], 0
	v_add_u32_e32 v2, 0xe000, v155
	ds_read2_b64 v[230:233], v2 offset0:224 offset1:228
	v_cvt_pk_bf16_f32 v41, v52, v53
	v_mfma_f32_16x16x32_bf16 v[190:193], v[28:31], v[20:23], 0
	ds_read2_b64 v[28:31], v140 offset0:96 offset1:100
	v_cvt_pk_bf16_f32 v42, v55, v163
	v_cvt_pk_bf16_f32 v40, v44, v45
	s_waitcnt lgkmcnt(0)
	v_mfma_f32_16x16x32_bf16 v[194:197], v[28:31], v[24:27], 0
	v_cvt_pk_bf16_f32 v44, v111, v114
	v_cvt_pk_bf16_f32 v45, v117, v122
	v_cvt_pk_bf16_f32 v46, v130, v135
	v_mfma_f32_16x16x32_bf16 v[198:201], v[28:31], v[20:23], 0
	ds_read2_b64 v[28:31], v144 offset0:128 offset1:132
	v_cvt_pk_bf16_f32 v47, v138, v142
	v_cvt_pk_bf16_f32 v43, v164, v43
	s_waitcnt lgkmcnt(0)
	v_mfma_f32_16x16x32_bf16 v[206:209], v[28:31], v[24:27], 0
	v_cvt_pk_bf16_f32 v48, v48, v50
	v_cvt_pk_bf16_f32 v49, v49, v51
	v_cvt_pk_bf16_f32 v50, v60, v61
	v_mfma_f32_16x16x32_bf16 v[210:213], v[28:31], v[20:23], 0
	ds_read2_b64 v[28:31], v149 offset0:160 offset1:164
	v_cvt_pk_bf16_f32 v51, v63, v162
	v_cvt_pk_bf16_f32 v56, v56, v58
	s_waitcnt lgkmcnt(0)
	v_mfma_f32_16x16x32_bf16 v[214:217], v[28:31], v[24:27], 0
	v_cvt_pk_bf16_f32 v57, v57, v59
	v_cvt_pk_bf16_f32 v58, v156, v157
	v_cvt_pk_bf16_f32 v59, v158, v159
	v_mfma_f32_16x16x32_bf16 v[218:221], v[28:31], v[20:23], 0
	ds_read2_b64 v[28:31], v150 offset0:192 offset1:196
	ds_read2_b64 v[156:159], v136 offset0:96 offset1:100
	v_add_f32_e32 v92, v0, v1
	s_waitcnt lgkmcnt(1)
	v_mfma_f32_16x16x32_bf16 v[222:225], v[28:31], v[24:27], 0
	v_cvt_pk_bf16_f32 v0, v4, v5
	v_cvt_pk_bf16_f32 v3, v11, v3
	v_cvt_pk_bf16_f32 v4, v12, v13
	v_mfma_f32_16x16x32_bf16 v[226:229], v[28:31], v[20:23], 0
	v_cvt_pk_bf16_f32 v31, v171, v172
	ds_read2_b64 v[170:173], v133 offset0:40 offset1:44
	v_cvt_pk_bf16_f32 v28, v62, v160
	v_cvt_pk_bf16_f32 v29, v54, v161
	v_cvt_pk_bf16_f32 v30, v166, v169
	v_mfma_f32_16x16x32_bf16 v[234:237], v[230:233], v[24:27], 0
	ds_read2_b64 v[52:55], v133 offset0:48 offset1:52
	ds_read2_b64 v[60:63], v133 offset0:56 offset1:60
	v_cvt_pk_bf16_f32 v1, v6, v7
	v_mfma_f32_16x16x32_bf16 v[166:169], v[238:241], v[28:31], v[174:177]
	v_cvt_pk_bf16_f32 v6, v16, v17
	v_cvt_pk_bf16_f32 v16, v36, v38
	v_cvt_pk_bf16_f32 v17, v37, v39
	s_waitcnt lgkmcnt(2)
	v_mfma_f32_16x16x32_bf16 v[174:177], v[170:173], v[32:35], v[178:181]
	v_cvt_pk_bf16_f32 v38, v77, v79
	v_cvt_pk_bf16_f32 v39, v81, v95
	v_cvt_pk_bf16_f32 v5, v14, v15
	ds_read2_b64 v[178:181], v136 offset0:72 offset1:76
	v_mfma_f32_16x16x32_bf16 v[170:173], v[170:173], v[28:31], v[182:185]
	v_cvt_pk_bf16_f32 v36, v66, v69
	v_cvt_pk_bf16_f32 v37, v71, v72
	v_cvt_pk_bf16_f32 v19, v94, v19
	s_waitcnt lgkmcnt(0)
	v_mfma_f32_16x16x32_bf16 v[182:185], v[178:181], v[32:35], v[186:189]
	s_nop 2
	ds_read2_b64 v[186:189], v140 offset0:104 offset1:108
	v_cvt_pk_bf16_f32 v7, v8, v9
	v_add_u32_e32 v96, v96, v109
	v_mfma_f32_16x16x32_bf16 v[178:181], v[178:181], v[28:31], v[190:193]
	v_add_u32_e32 v98, v98, v109
	s_mov_b32 s88, s84
	v_subrev_u32_e32 v96, s84, v96
	s_waitcnt lgkmcnt(0)
	v_mfma_f32_16x16x32_bf16 v[190:193], v[186:189], v[32:35], v[194:197]
	v_subrev_u32_e32 v98, s84, v98
	s_nop 1
	ds_read2_b64 v[194:197], v144 offset0:136 offset1:140
	v_add_u32_e32 v109, 0x1c0, v99
	v_mfma_f32_16x16x32_bf16 v[186:189], v[186:189], v[28:31], v[198:201]
	s_waitcnt lgkmcnt(0)
	v_mfma_f32_16x16x32_bf16 v[198:201], v[194:197], v[32:35], v[206:209]
	s_nop 2
	ds_read2_b64 v[206:209], v149 offset0:168 offset1:172
	v_mfma_f32_16x16x32_bf16 v[194:197], v[194:197], v[28:31], v[210:213]
	s_waitcnt lgkmcnt(0)
	v_mfma_f32_16x16x32_bf16 v[210:213], v[206:209], v[32:35], v[214:217]
	s_nop 2
	ds_read2_b64 v[214:217], v150 offset0:200 offset1:204
	v_mfma_f32_16x16x32_bf16 v[206:209], v[206:209], v[28:31], v[218:221]
	s_waitcnt lgkmcnt(0)
	v_mfma_f32_16x16x32_bf16 v[218:221], v[214:217], v[32:35], v[222:225]
	s_nop 2
	ds_read2_b64 v[222:225], v2 offset0:232 offset1:236
	v_mfma_f32_16x16x32_bf16 v[214:217], v[214:217], v[28:31], v[226:229]
	s_waitcnt lgkmcnt(0)
	v_mfma_f32_16x16x32_bf16 v[226:229], v[222:225], v[32:35], v[234:237]
	s_nop 2
	ds_read2_b64 v[234:237], v155 offset0:16 offset1:20
	s_waitcnt lgkmcnt(0)
	v_mfma_f32_16x16x32_bf16 v[164:167], v[234:237], v[40:43], v[166:169]
	v_mfma_f32_16x16x32_bf16 v[174:177], v[52:55], v[44:47], v[174:177]
	v_mfma_f32_16x16x32_bf16 v[168:171], v[52:55], v[40:43], v[170:173]
	ds_read2_b64 v[52:55], v136 offset0:80 offset1:84
	s_waitcnt lgkmcnt(0)
; #define LAS __attribute__((address_space(3)))
; #define MFMA16(a, b, c) __builtin_amdgcn_mfma_f32_16x16x32_bf16((a), (b), (c), 0, 0, 0)
; __device__ __forceinline__ void xattn_softmax(f32x4 (&s)[16], bf16x8 (&pf)[8], float& rinv) {
;     ...
;     sum += __shfl_xor(sum, 16); sum += __shfl_xor(sum, 32);
;     rinv = 1.f / sum;
; __device__ __forceinline__ void xattn_pair(LAS unsigned char* lds, int bh, size_t row_base, bf16* QO, const bf16* Kx, const bf16* VTx, int tid, const WsRef& wsr) {
;     ...
;     for (int nh = 0; nh < 2; ++nh) {
;         f32x4 o0[8], o1[8];
; #pragma unroll
;         for (int n = 0; n < 8; ++n) { o0[n] = (f32x4){0.f, 0.f, 0.f, 0.f}; o1[n] = (f32x4){0.f, 0.f, 0.f, 0.f}; }
; #pragma unroll
;         for (int kk = 0; kk < 8; ++kk)
; #pragma unroll
;             for (int n = 0; n < 8; ++n) { const LAS bf16* vp = T + ((nh * 8 + n) * 16 + fr) * LDX + kk * 32 + 4 * fq;
;                 const u32x2 lo = *(const LAS u32x2*)vp, hi = *(const LAS u32x2*)(vp + 16); u32x4 w; w.x = lo.x; w.y = lo.y; w.z = hi.x; w.w = hi.y; const bf16x8 vf = __builtin_bit_cast(bf16x8, w);
;                 o0[n] = MFMA16(vf, pf0[kk], o0[n]); o1[n] = MFMA16(vf, pf1[kk], o1[n]); }
	v_mfma_f32_16x16x32_bf16 v[182:185], v[52:55], v[44:47], v[182:185]
	v_mfma_f32_16x16x32_bf16 v[178:181], v[52:55], v[40:43], v[178:181]
	ds_read2_b64 v[52:55], v140 offset0:112 offset1:116
	s_waitcnt lgkmcnt(0)
	v_mfma_f32_16x16x32_bf16 v[190:193], v[52:55], v[44:47], v[190:193]
	v_mfma_f32_16x16x32_bf16 v[186:189], v[52:55], v[40:43], v[186:189]
	ds_read2_b64 v[52:55], v144 offset0:144 offset1:148
	s_waitcnt lgkmcnt(0)
	v_mfma_f32_16x16x32_bf16 v[198:201], v[52:55], v[44:47], v[198:201]
	v_mfma_f32_16x16x32_bf16 v[194:197], v[52:55], v[40:43], v[194:197]
	ds_read2_b64 v[52:55], v149 offset0:176 offset1:180
	v_mfma_f32_16x16x32_bf16 v[88:91], v[238:241], v[32:35], v[88:91]
	s_waitcnt lgkmcnt(0)
	v_mfma_f32_16x16x32_bf16 v[210:213], v[52:55], v[44:47], v[210:213]
	v_mfma_f32_16x16x32_bf16 v[206:209], v[52:55], v[40:43], v[206:209]
	ds_read2_b64 v[52:55], v150 offset0:208 offset1:212
	v_mfma_f32_16x16x32_bf16 v[88:91], v[234:237], v[44:47], v[88:91]
	ds_read2_b64 v[234:237], v155 offset0:24 offset1:28
	s_waitcnt lgkmcnt(1)
	v_mfma_f32_16x16x32_bf16 v[218:221], v[52:55], v[44:47], v[218:221]
	v_mfma_f32_16x16x32_bf16 v[214:217], v[52:55], v[40:43], v[214:217]
	v_cvt_pk_bf16_f32 v52, v83, v102
	v_cvt_pk_bf16_f32 v53, v110, v113
	v_cvt_pk_bf16_f32 v54, v120, v125
	v_cvt_pk_bf16_f32 v55, v129, v134
	s_waitcnt lgkmcnt(0)
	v_mfma_f32_16x16x32_bf16 v[160:163], v[234:237], v[48:51], v[164:167]
	v_add_f32_e32 v102, v153, v154
	ds_bpermute_b32 v114, v64, v102
	ds_bpermute_b32 v64, v64, v92
	v_mfma_f32_16x16x32_bf16 v[164:167], v[60:63], v[52:55], v[174:177]
	v_add_u32_e32 v129, 64, v99
	s_waitcnt lgkmcnt(1)
	v_add_f32_e32 v102, v102, v114
	v_mfma_f32_16x16x32_bf16 v[168:171], v[60:63], v[48:51], v[168:171]
	ds_read2_b64 v[60:63], v136 offset0:88 offset1:92
	s_waitcnt lgkmcnt(1)
	v_add_f32_e32 v14, v92, v64
	v_div_scale_f32 v15, s[8:9], v14, v14, 1.0
	s_waitcnt lgkmcnt(0)
	v_mfma_f32_16x16x32_bf16 v[172:175], v[60:63], v[52:55], v[182:185]
	v_rcp_f32_e32 v64, v15
	v_div_scale_f32 v72, s[8:9], v102, v102, 1.0
	v_mfma_f32_16x16x32_bf16 v[176:179], v[60:63], v[48:51], v[178:181]
	ds_read2_b64 v[60:63], v140 offset0:120 offset1:124
	v_fma_f32 v8, -v15, v64, 1.0
	v_fmac_f32_e32 v64, v8, v64
	s_waitcnt lgkmcnt(0)
	v_mfma_f32_16x16x32_bf16 v[180:183], v[60:63], v[52:55], v[190:193]
	v_div_scale_f32 v8, vcc, 1.0, v14, 1.0
	v_mul_f32_e32 v9, v8, v64
	v_mfma_f32_16x16x32_bf16 v[184:187], v[60:63], v[48:51], v[186:189]
	ds_read2_b64 v[60:63], v144 offset0:152 offset1:156
	v_rcp_f32_e32 v114, v72
	v_fma_f32 v66, -v15, v9, v8
	s_waitcnt lgkmcnt(0)
	v_mfma_f32_16x16x32_bf16 v[188:191], v[60:63], v[52:55], v[198:201]
	v_fmac_f32_e32 v9, v66, v64
	v_fma_f32 v8, -v15, v9, v8
	v_div_fmas_f32 v8, v8, v64, v9
	v_mfma_f32_16x16x32_bf16 v[192:195], v[60:63], v[48:51], v[194:197]
	ds_read2_b64 v[60:63], v149 offset0:184 offset1:188
	v_cvt_pk_bf16_f32 v15, v73, v75
	v_div_scale_f32 v73, vcc, 1.0, v102, 1.0
	s_waitcnt lgkmcnt(0)
	v_mfma_f32_16x16x32_bf16 v[196:199], v[60:63], v[52:55], v[210:213]
	v_cvt_pk_bf16_f32 v9, v126, v131
	v_mfma_f32_16x16x32_bf16 v[200:203], v[60:63], v[48:51], v[206:209]
	ds_read2_b64 v[60:63], v150 offset0:216 offset1:220
	v_mfma_f32_16x16x32_bf16 v[230:233], v[230:233], v[20:23], 0
	v_mfma_f32_16x16x32_bf16 v[222:225], v[222:225], v[28:31], v[230:233]
	s_waitcnt lgkmcnt(0)
	v_mfma_f32_16x16x32_bf16 v[210:213], v[60:63], v[48:51], v[214:217]
	s_nop 4
	ds_read2_b64 v[230:233], v2 offset0:240 offset1:244
	ds_read2_b64 v[214:217], v2 offset0:248 offset1:252
	s_waitcnt lgkmcnt(1)
	v_mfma_f32_16x16x32_bf16 v[226:229], v[230:233], v[44:47], v[226:229]
	v_cvt_pk_bf16_f32 v2, v10, v18
	ds_read2_b64 v[10:13], v155 offset0:40 offset1:44
	v_cvt_pk_bf16_f32 v18, v86, v87
	v_mfma_f32_16x16x32_bf16 v[206:209], v[60:63], v[52:55], v[218:221]
	v_cvt_pk_bf16_f32 v62, v112, v115
	ds_read2_b64 v[110:113], v133 offset0:64 offset1:68
	v_cvt_pk_bf16_f32 v60, v78, v80
	s_waitcnt lgkmcnt(2)
	v_mfma_f32_16x16x32_bf16 v[218:221], v[214:217], v[52:55], v[226:229]
	v_cvt_pk_bf16_f32 v61, v82, v100
	v_cvt_pk_bf16_f32 v63, v119, v124
	v_add_u32_e32 v115, 0xe800, v155
	ds_read2_b64 v[226:229], v155 offset0:32 offset1:36
	v_mfma_f32_16x16x32_bf16 v[88:91], v[234:237], v[52:55], v[88:91]
	ds_read2_b64 v[78:81], v133 offset0:72 offset1:76
	v_div_fixup_f32 v100, v8, v14, 1.0
	v_cvt_pk_bf16_f32 v8, v116, v121
	s_waitcnt lgkmcnt(2)
	v_mfma_f32_16x16x32_bf16 v[122:125], v[110:113], v[60:63], v[164:167]
	v_cvt_pk_bf16_f32 v14, v74, v76
	s_nop 1
	ds_read2_b64 v[164:167], v140 offset0:128 offset1:132
	s_waitcnt lgkmcnt(2)
	v_mfma_f32_16x16x32_bf16 v[82:85], v[226:229], v[60:63], v[88:91]
	v_mfma_f32_16x16x32_bf16 v[88:91], v[226:229], v[56:59], v[160:163]
	v_mfma_f32_16x16x32_bf16 v[160:163], v[156:159], v[60:63], v[172:175]
	s_nop 2
	ds_read2_b64 v[172:175], v144 offset0:160 offset1:164
	v_mfma_f32_16x16x32_bf16 v[110:113], v[110:113], v[56:59], v[168:171]
	s_waitcnt lgkmcnt(1)
	v_mfma_f32_16x16x32_bf16 v[168:171], v[164:167], v[60:63], v[180:183]
	v_mfma_f32_16x16x32_bf16 v[164:167], v[164:167], v[56:59], v[184:187]
	s_nop 1
	ds_read2_b64 v[180:183], v149 offset0:192 offset1:196
	ds_read2_b64 v[184:187], v150 offset0:224 offset1:228
	v_mfma_f32_16x16x32_bf16 v[156:159], v[156:159], v[56:59], v[176:179]
	s_waitcnt lgkmcnt(2)
	v_mfma_f32_16x16x32_bf16 v[176:179], v[172:175], v[60:63], v[188:191]
	v_mfma_f32_16x16x32_bf16 v[172:175], v[172:175], v[56:59], v[192:195]
	s_nop 2
	ds_read2_b64 v[192:195], v115 offset1:4
	v_mfma_f32_16x16x32_bf16 v[222:225], v[230:233], v[40:43], v[222:225]
	v_mfma_f32_16x16x32_bf16 v[214:217], v[214:217], v[48:51], v[222:225]
	s_waitcnt lgkmcnt(2)
; #define LAS __attribute__((address_space(3)))
; __device__ __forceinline__ unsigned pk2(float lo, float hi) { return pg8::cvt_pk_bf16(lo, hi); }
; __device__ __forceinline__ void wt_store8(const WsRef& w, const void* p, u32x2 v) { __builtin_amdgcn_raw_buffer_store_b64(v, w.r, (unsigned)((const unsigned char*)p - w.base), 0, 16); }
; #define MFMA16(a, b, c) __builtin_amdgcn_mfma_f32_16x16x32_bf16((a), (b), (c), 0, 0, 0)
; __device__ __forceinline__ void xattn_pair(LAS unsigned char* lds, int bh, size_t row_base, bf16* QO, const bf16* Kx, const bf16* VTx, int tid, const WsRef& wsr) {
;     ...
;     for (int nh = 0; nh < 2; ++nh) {
;         f32x4 o0[8], o1[8];
; #pragma unroll
;         for (int n = 0; n < 8; ++n) { o0[n] = (f32x4){0.f, 0.f, 0.f, 0.f}; o1[n] = (f32x4){0.f, 0.f, 0.f, 0.f}; }
; #pragma unroll
;         for (int kk = 0; kk < 8; ++kk)
; #pragma unroll
;             for (int n = 0; n < 8; ++n) { const LAS bf16* vp = T + ((nh * 8 + n) * 16 + fr) * LDX + kk * 32 + 4 * fq;
;                 const u32x2 lo = *(const LAS u32x2*)vp, hi = *(const LAS u32x2*)(vp + 16); u32x4 w; w.x = lo.x; w.y = lo.y; w.z = hi.x; w.w = hi.y; const bf16x8 vf = __builtin_bit_cast(bf16x8, w);
;                 o0[n] = MFMA16(vf, pf0[kk], o0[n]); o1[n] = MFMA16(vf, pf1[kk], o1[n]); }
; #pragma unroll
;         for (int n = 0; n < 8; ++n) { const f32x4 v0 = o0[n] * rinv0, v1 = o1[n] * rinv1; u32x2 w0, w1; w0.x = pk2(v0[0], v0[1]); w0.y = pk2(v0[2], v0[3]); w1.x = pk2(v1[0], v1[1]); w1.y = pk2(v1[2], v1[3]);
;             wt_store8(wsr, qp0 + (nh * 8 + n) * 16 + 4 * fq, w0); wt_store8(wsr, qp1 + (nh * 8 + n) * 16 + 4 * fq, w1); }
	v_mfma_f32_16x16x32_bf16 v[188:191], v[180:183], v[60:63], v[196:199]
	s_waitcnt lgkmcnt(1)
	v_mfma_f32_16x16x32_bf16 v[196:199], v[184:187], v[60:63], v[206:209]
	v_mfma_f32_16x16x32_bf16 v[184:187], v[184:187], v[56:59], v[210:213]
	v_mfma_f32_16x16x32_bf16 v[206:209], v[10:13], v[36:39], v[82:85]
	v_mfma_f32_16x16x32_bf16 v[210:213], v[10:13], v[16:19], v[88:91]
	ds_read2_b64 v[10:13], v136 offset0:104 offset1:108
	s_nop 0
	ds_read2_b64 v[82:85], v144 offset0:168 offset1:172
	v_mfma_f32_16x16x32_bf16 v[180:183], v[180:183], v[56:59], v[200:203]
	s_waitcnt lgkmcnt(2)
	v_mfma_f32_16x16x32_bf16 v[200:203], v[192:195], v[60:63], v[218:221]
	v_mfma_f32_16x16x32_bf16 v[192:195], v[192:195], v[56:59], v[214:217]
	v_mfma_f32_16x16x32_bf16 v[122:125], v[78:81], v[36:39], v[122:125]
	v_mfma_f32_16x16x32_bf16 v[214:217], v[78:81], v[16:19], v[110:113]
	ds_read2_b64 v[78:81], v140 offset0:136 offset1:140
	s_nop 1
	ds_read2_b64 v[110:113], v149 offset0:200 offset1:204
	s_waitcnt lgkmcnt(3)
	v_mfma_f32_16x16x32_bf16 v[160:163], v[10:13], v[36:39], v[160:163]
	v_mfma_f32_16x16x32_bf16 v[156:159], v[10:13], v[16:19], v[156:159]
	v_cvt_pk_bf16_f32 v12, v65, v68
	v_cvt_pk_bf16_f32 v13, v67, v70
	ds_read2_b64 v[64:67], v150 offset0:232 offset1:236
	v_fma_f32 v68, -v72, v114, 1.0
	s_waitcnt lgkmcnt(3)
	v_mfma_f32_16x16x32_bf16 v[88:91], v[82:85], v[16:19], v[172:175]
	v_fmac_f32_e32 v114, v68, v114
	ds_read2_b64 v[68:71], v115 offset0:8 offset1:12
	v_cvt_pk_bf16_f32 v10, v137, v141
	ds_read2_b64 v[172:175], v133 offset0:80 offset1:84
	s_waitcnt lgkmcnt(4)
	v_mfma_f32_16x16x32_bf16 v[116:119], v[78:81], v[16:19], v[164:167]
	v_cvt_pk_bf16_f32 v11, v145, v147
	s_nop 1
	ds_read2_b64 v[164:167], v155 offset0:48 offset1:52
	v_mfma_f32_16x16x32_bf16 v[168:171], v[78:81], v[36:39], v[168:171]
	v_mfma_f32_16x16x32_bf16 v[92:95], v[82:85], v[36:39], v[176:179]
	s_waitcnt lgkmcnt(4)
	v_mfma_f32_16x16x32_bf16 v[80:83], v[110:113], v[36:39], v[188:191]
	v_mfma_f32_16x16x32_bf16 v[84:87], v[110:113], v[16:19], v[180:183]
	v_mul_f32_e32 v110, v73, v114
	v_fma_f32 v74, -v72, v110, v73
	v_fmac_f32_e32 v110, v74, v114
	v_fma_f32 v111, -v72, v110, v73
	s_waitcnt lgkmcnt(3)
	v_mfma_f32_16x16x32_bf16 v[76:79], v[64:67], v[36:39], v[196:199]
	v_add_u32_e32 v113, 0xc0, v99
	v_add_u32_e32 v112, 0x100, v99
	v_mfma_f32_16x16x32_bf16 v[72:75], v[64:67], v[16:19], v[184:187]
	v_div_fmas_f32 v64, v111, v114, v110
	v_div_fixup_f32 v102, v64, v102, 1.0
	ds_read2_b64 v[180:183], v136 offset0:112 offset1:116
	ds_read2_b64 v[184:187], v140 offset0:144 offset1:148
	ds_read2_b64 v[188:191], v144 offset0:176 offset1:180
	s_waitcnt lgkmcnt(5)
	v_mfma_f32_16x16x32_bf16 v[64:67], v[68:71], v[36:39], v[200:203]
	v_add_u32_e32 v114, 0x80, v99
	v_add_u32_e32 v111, 0x140, v99
	v_add_u32_e32 v110, 0x180, v99
	v_mfma_f32_16x16x32_bf16 v[68:71], v[68:71], v[16:19], v[192:195]
	s_waitcnt lgkmcnt(4)
	v_mfma_f32_16x16x32_bf16 v[120:123], v[172:175], v[12:15], v[122:125]
	s_nop 2
	ds_read2_b64 v[124:127], v149 offset0:208 offset1:212
	ds_read2_b64 v[192:195], v150 offset0:240 offset1:244
	ds_read2_b64 v[152:155], v155 offset0:56 offset1:60
	ds_read2_b64 v[130:133], v133 offset0:88 offset1:92
	ds_read2_b64 v[196:199], v115 offset0:16 offset1:20
	s_waitcnt lgkmcnt(8)
	v_mfma_f32_16x16x32_bf16 v[176:179], v[164:167], v[12:15], v[206:209]
	ds_read2_b64 v[134:137], v136 offset0:120 offset1:124
	ds_read2_b64 v[138:141], v140 offset0:152 offset1:156
	ds_read2_b64 v[142:145], v144 offset0:184 offset1:188
	ds_read2_b64 v[146:149], v149 offset0:216 offset1:220
	ds_read2_b64 v[200:203], v150 offset0:248 offset1:252
	ds_read2_b64 v[206:209], v115 offset0:24 offset1:28
	v_mfma_f32_16x16x32_bf16 v[164:167], v[164:167], v[4:7], v[210:213]
	s_waitcnt lgkmcnt(8)
	v_mfma_f32_16x16x32_bf16 v[176:179], v[152:155], v[8:11], v[176:179]
	v_mfma_f32_16x16x32_bf16 v[150:153], v[152:155], v[0:3], v[164:167]
	v_mfma_f32_16x16x32_bf16 v[172:175], v[172:175], v[4:7], v[214:217]
	s_nop 5
	v_mul_f32_e64 v164, v102, v178
	v_mul_f32_e64 v165, v102, v179
	v_pk_mul_f32 v[166:167], v[102:103], v[176:177] op_sel_hi:[0,1]
	v_pk_mul_f32 v[176:177], v[100:101], v[152:153] op_sel_hi:[0,1]
	s_waitcnt lgkmcnt(7)
	v_mfma_f32_16x16x32_bf16 v[120:123], v[130:133], v[8:11], v[120:123]
	v_mul_f32_e64 v150, v100, v150
	v_mul_f32_e64 v151, v100, v151
	v_cvt_pk_bf16_f32 v166, v166, v167
	v_cvt_pk_bf16_f32 v167, v164, v165
	v_cvt_pk_bf16_f32 v150, v150, v151
	v_cvt_pk_bf16_f32 v151, v176, v177
	v_readlane_b32 vcc_lo, v255, 59
	s_mov_b32 vcc_hi, 0
	s_nop 1
	s_mov_b64 vcc, vcc
	s_nop 1
	s_cbranch_vccnz .Lpp8_plain
; #define LAS __attribute__((address_space(3)))
; __device__ __forceinline__ unsigned pk2(float lo, float hi) { return pg8::cvt_pk_bf16(lo, hi); }
; #define MFMA16(a, b, c) __builtin_amdgcn_mfma_f32_16x16x32_bf16((a), (b), (c), 0, 0, 0)
; __device__ __forceinline__ void wt_store8(const WsRef& w, const void* p, u32x2 v) { __builtin_amdgcn_raw_buffer_store_b64(v, w.r, (unsigned)((const unsigned char*)p - w.base), 0, 16); }
; __device__ __forceinline__ void wt_store16(const WsRef& w, const void* p, u32x4 v) { __builtin_amdgcn_raw_buffer_store_b128(v, w.r, (unsigned)((const unsigned char*)p - w.base), 0, 16); }
; __device__ __forceinline__ void xattn_pair(LAS unsigned char* lds, int bh, size_t row_base, bf16* QO, const bf16* Kx, const bf16* VTx, int tid, const WsRef& wsr) {
;     ...
;     for (int nh = 0; nh < 2; ++nh) {
;         f32x4 o0[8], o1[8];
; #pragma unroll
;         for (int n = 0; n < 8; ++n) { o0[n] = (f32x4){0.f, 0.f, 0.f, 0.f}; o1[n] = (f32x4){0.f, 0.f, 0.f, 0.f}; }
; #pragma unroll
;         for (int kk = 0; kk < 8; ++kk)
; #pragma unroll
;             for (int n = 0; n < 8; ++n) { const LAS bf16* vp = T + ((nh * 8 + n) * 16 + fr) * LDX + kk * 32 + 4 * fq;
;                 const u32x2 lo = *(const LAS u32x2*)vp, hi = *(const LAS u32x2*)(vp + 16); u32x4 w; w.x = lo.x; w.y = lo.y; w.z = hi.x; w.w = hi.y; const bf16x8 vf = __builtin_bit_cast(bf16x8, w);
;                 o0[n] = MFMA16(vf, pf0[kk], o0[n]); o1[n] = MFMA16(vf, pf1[kk], o1[n]); }
; #pragma unroll
;         for (int n = 0; n < 8; ++n) { const f32x4 v0 = o0[n] * rinv0, v1 = o1[n] * rinv1; u32x2 w0, w1; w0.x = pk2(v0[0], v0[1]); w0.y = pk2(v0[2], v0[3]); w1.x = pk2(v1[0], v1[1]); w1.y = pk2(v1[2], v1[3]);
;             wt_store8(wsr, qp0 + (nh * 8 + n) * 16 + 4 * fq, w0); wt_store8(wsr, qp1 + (nh * 8 + n) * 16 + 4 * fq, w1); }
;         __builtin_amdgcn_sched_barrier(0);
	buffer_store_dwordx2 v[166:167], v96, s[88:91], 0 offen sc1
	buffer_store_dwordx2 v[150:151], v98, s[88:91], 0 offen sc1
	v_pk_mul_f32 v[150:151], v[102:103], v[122:123] op_sel_hi:[0,1]
	v_pk_mul_f32 v[164:165], v[102:103], v[120:121] op_sel_hi:[0,1]
	v_mfma_f32_16x16x32_bf16 v[120:123], v[130:133], v[0:3], v[172:175]
	v_cvt_pk_bf16_f32 v130, v164, v165
	v_cvt_pk_bf16_f32 v131, v150, v151
	v_mfma_f32_16x16x32_bf16 v[160:163], v[180:183], v[12:15], v[160:163]
	v_mfma_f32_16x16x32_bf16 v[152:155], v[180:183], v[4:7], v[156:159]
	s_nop 3
	v_mul_f32_e64 v122, v100, v122
	v_mul_f32_e64 v123, v100, v123
	v_pk_mul_f32 v[120:121], v[100:101], v[120:121] op_sel_hi:[0,1]
	v_cvt_pk_bf16_f32 v132, v120, v121
	v_cvt_pk_bf16_f32 v133, v122, v123
	s_waitcnt lgkmcnt(5)
	v_mfma_f32_16x16x32_bf16 v[120:123], v[134:137], v[8:11], v[160:163]
	buffer_store_dwordx2 v[130:131], v96, s[88:91], 0 offen offset:32 sc1
	buffer_store_dwordx2 v[132:133], v98, s[88:91], 0 offen offset:32 sc1
	v_mfma_f32_16x16x32_bf16 v[156:159], v[184:187], v[12:15], v[168:171]
	s_nop 4
	v_mul_f32_e64 v122, v102, v122
	v_mul_f32_e64 v123, v102, v123
	v_pk_mul_f32 v[120:121], v[102:103], v[120:121] op_sel_hi:[0,1]
	v_mfma_f32_16x16x32_bf16 v[116:119], v[184:187], v[4:7], v[116:119]
	v_mfma_f32_16x16x32_bf16 v[92:95], v[188:191], v[12:15], v[92:95]
	v_mfma_f32_16x16x32_bf16 v[88:91], v[188:191], v[4:7], v[88:91]
	v_mfma_f32_16x16x32_bf16 v[80:83], v[124:127], v[12:15], v[80:83]
	v_mfma_f32_16x16x32_bf16 v[130:133], v[134:137], v[0:3], v[152:155]
	v_cvt_pk_bf16_f32 v134, v120, v121
	v_cvt_pk_bf16_f32 v135, v122, v123
	s_waitcnt lgkmcnt(4)
	v_mfma_f32_16x16x32_bf16 v[120:123], v[138:141], v[8:11], v[156:159]
	v_mfma_f32_16x16x32_bf16 v[116:119], v[138:141], v[0:3], v[116:119]
	s_nop 2
	v_mul_f32_e64 v132, v100, v132
	v_mul_f32_e64 v133, v100, v133
	s_nop 1
	v_pk_mul_f32 v[122:123], v[102:103], v[122:123] op_sel_hi:[0,1]
	v_pk_mul_f32 v[120:121], v[102:103], v[120:121] op_sel_hi:[0,1]
	s_waitcnt lgkmcnt(3)
	v_mfma_f32_16x16x32_bf16 v[92:95], v[142:145], v[8:11], v[92:95]
	v_mul_f32_e64 v130, v100, v130
	v_mul_f32_e64 v131, v100, v131
	v_pk_mul_f32 v[118:119], v[100:101], v[118:119] op_sel_hi:[0,1]
	v_pk_mul_f32 v[116:117], v[100:101], v[116:117] op_sel_hi:[0,1]
	v_mfma_f32_16x16x32_bf16 v[88:91], v[142:145], v[0:3], v[88:91]
	v_cvt_pk_bf16_f32 v120, v120, v121
	s_nop 1
	v_pk_mul_f32 v[94:95], v[102:103], v[94:95] op_sel_hi:[0,1]
	v_pk_mul_f32 v[92:93], v[102:103], v[92:93] op_sel_hi:[0,1]
	v_mfma_f32_16x16x32_bf16 v[76:79], v[192:195], v[12:15], v[76:79]
	v_cvt_pk_bf16_f32 v121, v122, v123
	s_nop 0
	v_pk_mul_f32 v[90:91], v[100:101], v[90:91] op_sel_hi:[0,1]
	v_pk_mul_f32 v[88:89], v[100:101], v[88:89] op_sel_hi:[0,1]
	v_mfma_f32_16x16x32_bf16 v[72:75], v[192:195], v[4:7], v[72:75]
	v_cvt_pk_bf16_f32 v116, v116, v117
	v_cvt_pk_bf16_f32 v117, v118, v119
	v_cvt_pk_bf16_f32 v92, v92, v93
	v_mfma_f32_16x16x32_bf16 v[84:87], v[124:127], v[4:7], v[84:87]
	v_cvt_pk_bf16_f32 v93, v94, v95
	v_cvt_pk_bf16_f32 v88, v88, v89
	v_cvt_pk_bf16_f32 v89, v90, v91
	s_waitcnt lgkmcnt(2)
	v_mfma_f32_16x16x32_bf16 v[80:83], v[146:149], v[8:11], v[80:83]
	v_cvt_pk_bf16_f32 v130, v130, v131
	v_cvt_pk_bf16_f32 v131, v132, v133
	buffer_store_dwordx2 v[134:135], v96, s[88:91], 0 offen offset:64 sc1
	buffer_store_dwordx2 v[130:131], v98, s[88:91], 0 offen offset:64 sc1
	v_mfma_f32_16x16x32_bf16 v[64:67], v[196:199], v[12:15], v[64:67]
	buffer_store_dwordx2 v[120:121], v96, s[88:91], 0 offen offset:96 sc1
	buffer_store_dwordx2 v[116:117], v98, s[88:91], 0 offen offset:96 sc1
	buffer_store_dwordx2 v[92:93], v96, s[88:91], 0 offen offset:128 sc1
	buffer_store_dwordx2 v[88:89], v98, s[88:91], 0 offen offset:128 sc1
	s_waitcnt lgkmcnt(1)
	v_mfma_f32_16x16x32_bf16 v[76:79], v[200:203], v[8:11], v[76:79]
	v_mul_f32_e64 v88, v102, v82
	v_mul_f32_e64 v89, v102, v83
	v_pk_mul_f32 v[80:81], v[102:103], v[80:81] op_sel_hi:[0,1]
	v_cvt_pk_bf16_f32 v80, v80, v81
	v_mfma_f32_16x16x32_bf16 v[72:75], v[200:203], v[0:3], v[72:75]
	v_cvt_pk_bf16_f32 v81, v88, v89
	s_nop 1
	v_pk_mul_f32 v[78:79], v[102:103], v[78:79] op_sel_hi:[0,1]
	v_pk_mul_f32 v[76:77], v[102:103], v[76:77] op_sel_hi:[0,1]
	v_mfma_f32_16x16x32_bf16 v[82:85], v[146:149], v[0:3], v[84:87]
	v_cvt_pk_bf16_f32 v76, v76, v77
	s_nop 0
	v_pk_mul_f32 v[74:75], v[100:101], v[74:75] op_sel_hi:[0,1]
	v_pk_mul_f32 v[72:73], v[100:101], v[72:73] op_sel_hi:[0,1]
	v_mfma_f32_16x16x32_bf16 v[68:71], v[196:199], v[4:7], v[68:71]
	v_cvt_pk_bf16_f32 v77, v78, v79
	s_nop 1
	v_pk_mul_f32 v[84:85], v[100:101], v[84:85] op_sel_hi:[0,1]
	v_pk_mul_f32 v[82:83], v[100:101], v[82:83] op_sel_hi:[0,1]
	s_waitcnt lgkmcnt(0)
	v_mfma_f32_16x16x32_bf16 v[64:67], v[206:209], v[8:11], v[64:67]
	v_cvt_pk_bf16_f32 v72, v72, v73
	v_cvt_pk_bf16_f32 v73, v74, v75
	v_cvt_pk_bf16_f32 v82, v82, v83
	v_cvt_pk_bf16_f32 v83, v84, v85
	buffer_store_dwordx2 v[80:81], v96, s[88:91], 0 offen offset:160 sc1
	buffer_store_dwordx2 v[82:83], v98, s[88:91], 0 offen offset:160 sc1
	buffer_store_dwordx2 v[76:77], v96, s[88:91], 0 offen offset:192 sc1
	buffer_store_dwordx2 v[72:73], v98, s[88:91], 0 offen offset:192 sc1
	v_pk_mul_f32 v[72:73], v[102:103], v[66:67] op_sel_hi:[0,1]
	v_pk_mul_f32 v[74:75], v[102:103], v[64:65] op_sel_hi:[0,1]
	v_mfma_f32_16x16x32_bf16 v[64:67], v[206:209], v[0:3], v[68:71]
	s_nop 2
	v_cvt_pk_bf16_f32 v68, v74, v75
	v_cvt_pk_bf16_f32 v69, v72, v73
	s_nop 2
	v_pk_mul_f32 v[66:67], v[100:101], v[66:67] op_sel_hi:[0,1]
	v_pk_mul_f32 v[64:65], v[100:101], v[64:65] op_sel_hi:[0,1]
	v_cvt_pk_bf16_f32 v64, v64, v65
	v_cvt_pk_bf16_f32 v65, v66, v67
	buffer_store_dwordx2 v[68:69], v96, s[88:91], 0 offen offset:224 sc1
	buffer_store_dwordx2 v[64:65], v98, s[88:91], 0 offen offset:224 sc1
	v_add_u32_e32 v115, v99, v107
	ds_read2_b64 v[116:119], v115 offset1:4
	v_add_u32_e32 v115, v99, v105
	v_add_u32_e32 v64, v99, v97
	v_add_u32_e32 v72, v99, v103
	v_add_u32_e32 v80, v99, v106
	v_add_u32_e32 v88, v99, v108
	ds_read2_b64 v[124:127], v115 offset1:4
	v_add_u32_e32 v115, v99, v104
	v_add_u32_e32 v99, v99, v101
	ds_read2_b64 v[64:67], v64 offset1:4
	ds_read2_b64 v[72:75], v72 offset1:4
	ds_read2_b64 v[80:83], v80 offset1:4
	ds_read2_b64 v[88:91], v88 offset1:4
	ds_read2_b64 v[134:137], v115 offset1:4
	ds_read2_b64 v[142:145], v99 offset1:4
	v_add_u32_e32 v99, v129, v97
	s_waitcnt lgkmcnt(5)
; #define LAS __attribute__((address_space(3)))
; #define MFMA16(a, b, c) __builtin_amdgcn_mfma_f32_16x16x32_bf16((a), (b), (c), 0, 0, 0)
; __device__ __forceinline__ void xattn_pair(LAS unsigned char* lds, int bh, size_t row_base, bf16* QO, const bf16* Kx, const bf16* VTx, int tid, const WsRef& wsr) {
;     ...
;     for (int nh = 0; nh < 2; ++nh) {
;         f32x4 o0[8], o1[8];
; #pragma unroll
;         for (int n = 0; n < 8; ++n) { o0[n] = (f32x4){0.f, 0.f, 0.f, 0.f}; o1[n] = (f32x4){0.f, 0.f, 0.f, 0.f}; }
; #pragma unroll
;         for (int kk = 0; kk < 8; ++kk)
; #pragma unroll
;             for (int n = 0; n < 8; ++n) { const LAS bf16* vp = T + ((nh * 8 + n) * 16 + fr) * LDX + kk * 32 + 4 * fq;
;                 const u32x2 lo = *(const LAS u32x2*)vp, hi = *(const LAS u32x2*)(vp + 16); u32x4 w; w.x = lo.x; w.y = lo.y; w.z = hi.x; w.w = hi.y; const bf16x8 vf = __builtin_bit_cast(bf16x8, w);
;                 o0[n] = MFMA16(vf, pf0[kk], o0[n]); o1[n] = MFMA16(vf, pf1[kk], o1[n]); }
	v_mfma_f32_16x16x32_bf16 v[68:71], v[64:67], v[24:27], 0
	v_mfma_f32_16x16x32_bf16 v[64:67], v[64:67], v[20:23], 0
	s_waitcnt lgkmcnt(4)
	v_mfma_f32_16x16x32_bf16 v[76:79], v[72:75], v[24:27], 0
	v_mfma_f32_16x16x32_bf16 v[72:75], v[72:75], v[20:23], 0
	s_waitcnt lgkmcnt(3)
	v_mfma_f32_16x16x32_bf16 v[84:87], v[80:83], v[24:27], 0
	v_mfma_f32_16x16x32_bf16 v[80:83], v[80:83], v[20:23], 0
	s_waitcnt lgkmcnt(2)
	v_mfma_f32_16x16x32_bf16 v[92:95], v[88:91], v[24:27], 0
	v_mfma_f32_16x16x32_bf16 v[88:91], v[88:91], v[20:23], 0
	v_mfma_f32_16x16x32_bf16 v[120:123], v[116:119], v[24:27], 0
	v_mfma_f32_16x16x32_bf16 v[116:119], v[116:119], v[20:23], 0
	v_mfma_f32_16x16x32_bf16 v[130:133], v[124:127], v[24:27], 0
	v_mfma_f32_16x16x32_bf16 v[124:127], v[124:127], v[20:23], 0
	s_waitcnt lgkmcnt(1)
	v_mfma_f32_16x16x32_bf16 v[138:141], v[134:137], v[24:27], 0
	v_mfma_f32_16x16x32_bf16 v[134:137], v[134:137], v[20:23], 0
	s_waitcnt lgkmcnt(0)
	v_mfma_f32_16x16x32_bf16 v[24:27], v[142:145], v[24:27], 0
	v_mfma_f32_16x16x32_bf16 v[20:23], v[142:145], v[20:23], 0
	ds_read2_b64 v[142:145], v99 offset1:4
	v_add_u32_e32 v99, v129, v103
	s_waitcnt lgkmcnt(0)
	v_mfma_f32_16x16x32_bf16 v[68:71], v[142:145], v[32:35], v[68:71]
	v_mfma_f32_16x16x32_bf16 v[64:67], v[142:145], v[28:31], v[64:67]
	ds_read2_b64 v[142:145], v99 offset1:4
	v_add_u32_e32 v99, v129, v106
	s_waitcnt lgkmcnt(0)
	v_mfma_f32_16x16x32_bf16 v[76:79], v[142:145], v[32:35], v[76:79]
	v_mfma_f32_16x16x32_bf16 v[72:75], v[142:145], v[28:31], v[72:75]
	ds_read2_b64 v[142:145], v99 offset1:4
	v_add_u32_e32 v99, v129, v108
	s_waitcnt lgkmcnt(0)
	v_mfma_f32_16x16x32_bf16 v[84:87], v[142:145], v[32:35], v[84:87]
	v_mfma_f32_16x16x32_bf16 v[80:83], v[142:145], v[28:31], v[80:83]
	ds_read2_b64 v[142:145], v99 offset1:4
	v_add_u32_e32 v99, v129, v107
	s_waitcnt lgkmcnt(0)
	v_mfma_f32_16x16x32_bf16 v[92:95], v[142:145], v[32:35], v[92:95]
	v_mfma_f32_16x16x32_bf16 v[88:91], v[142:145], v[28:31], v[88:91]
	ds_read2_b64 v[142:145], v99 offset1:4
	v_add_u32_e32 v99, v129, v105
	s_waitcnt lgkmcnt(0)
	v_mfma_f32_16x16x32_bf16 v[120:123], v[142:145], v[32:35], v[120:123]
	v_mfma_f32_16x16x32_bf16 v[116:119], v[142:145], v[28:31], v[116:119]
	ds_read2_b64 v[142:145], v99 offset1:4
	v_add_u32_e32 v99, v129, v104
	s_waitcnt lgkmcnt(0)
	v_mfma_f32_16x16x32_bf16 v[130:133], v[142:145], v[32:35], v[130:133]
	v_mfma_f32_16x16x32_bf16 v[124:127], v[142:145], v[28:31], v[124:127]
	ds_read2_b64 v[142:145], v99 offset1:4
	v_add_u32_e32 v99, v129, v101
	s_waitcnt lgkmcnt(0)
	v_mfma_f32_16x16x32_bf16 v[138:141], v[142:145], v[32:35], v[138:141]
	v_mfma_f32_16x16x32_bf16 v[134:137], v[142:145], v[28:31], v[134:137]
	ds_read2_b64 v[142:145], v99 offset1:4
	v_add_u32_e32 v99, v114, v105
	s_waitcnt lgkmcnt(0)
	v_mfma_f32_16x16x32_bf16 v[20:23], v[142:145], v[28:31], v[20:23]
	v_add_u32_e32 v28, v114, v97
	ds_read2_b64 v[28:31], v28 offset1:4
	v_mfma_f32_16x16x32_bf16 v[24:27], v[142:145], v[32:35], v[24:27]
	s_waitcnt lgkmcnt(0)
	v_mfma_f32_16x16x32_bf16 v[32:35], v[28:31], v[44:47], v[68:71]
	v_mfma_f32_16x16x32_bf16 v[28:31], v[28:31], v[40:43], v[64:67]
	s_nop 2
	v_add_u32_e32 v64, v114, v103
	ds_read2_b64 v[64:67], v64 offset1:4
	s_waitcnt lgkmcnt(0)
	v_mfma_f32_16x16x32_bf16 v[68:71], v[64:67], v[44:47], v[76:79]
	v_mfma_f32_16x16x32_bf16 v[64:67], v[64:67], v[40:43], v[72:75]
	s_nop 2
	v_add_u32_e32 v72, v114, v106
	ds_read2_b64 v[72:75], v72 offset1:4
	s_waitcnt lgkmcnt(0)
	v_mfma_f32_16x16x32_bf16 v[76:79], v[72:75], v[44:47], v[84:87]
	v_mfma_f32_16x16x32_bf16 v[72:75], v[72:75], v[40:43], v[80:83]
	s_nop 2
	v_add_u32_e32 v80, v114, v108
	ds_read2_b64 v[80:83], v80 offset1:4
	s_waitcnt lgkmcnt(0)
	v_mfma_f32_16x16x32_bf16 v[84:87], v[80:83], v[44:47], v[92:95]
	v_mfma_f32_16x16x32_bf16 v[80:83], v[80:83], v[40:43], v[88:91]
	s_nop 2
	v_add_u32_e32 v88, v114, v107
	ds_read2_b64 v[88:91], v88 offset1:4
	s_waitcnt lgkmcnt(0)
	v_mfma_f32_16x16x32_bf16 v[92:95], v[88:91], v[44:47], v[120:123]
	v_mfma_f32_16x16x32_bf16 v[88:91], v[88:91], v[40:43], v[116:119]
	s_nop 2
	ds_read2_b64 v[116:119], v99 offset1:4
	v_add_u32_e32 v99, v114, v104
	s_waitcnt lgkmcnt(0)
	v_mfma_f32_16x16x32_bf16 v[120:123], v[116:119], v[44:47], v[130:133]
	v_mfma_f32_16x16x32_bf16 v[116:119], v[116:119], v[40:43], v[124:127]
	s_nop 2
	ds_read2_b64 v[124:127], v99 offset1:4
	v_add_u32_e32 v99, v114, v101
	s_waitcnt lgkmcnt(0)
	v_mfma_f32_16x16x32_bf16 v[130:133], v[124:127], v[44:47], v[138:141]
	v_mfma_f32_16x16x32_bf16 v[124:127], v[124:127], v[40:43], v[134:137]
	s_nop 2
	ds_read2_b64 v[134:137], v99 offset1:4
	s_waitcnt lgkmcnt(0)
	v_mfma_f32_16x16x32_bf16 v[20:23], v[134:137], v[40:43], v[20:23]
	v_add_u32_e32 v40, v113, v97
	ds_read2_b64 v[40:43], v40 offset1:4
	v_add_u32_e32 v99, v113, v104
	s_waitcnt lgkmcnt(0)
	v_mfma_f32_16x16x32_bf16 v[32:35], v[40:43], v[52:55], v[32:35]
	v_mfma_f32_16x16x32_bf16 v[28:31], v[40:43], v[48:51], v[28:31]
	v_add_u32_e32 v40, v113, v103
	ds_read2_b64 v[40:43], v40 offset1:4
	v_mfma_f32_16x16x32_bf16 v[24:27], v[134:137], v[44:47], v[24:27]
	s_waitcnt lgkmcnt(0)
	v_mfma_f32_16x16x32_bf16 v[44:47], v[40:43], v[52:55], v[68:71]
	v_mfma_f32_16x16x32_bf16 v[40:43], v[40:43], v[48:51], v[64:67]
	s_nop 2
	v_add_u32_e32 v64, v113, v106
	ds_read2_b64 v[64:67], v64 offset1:4
	s_waitcnt lgkmcnt(0)
	v_mfma_f32_16x16x32_bf16 v[68:71], v[64:67], v[52:55], v[76:79]
	v_mfma_f32_16x16x32_bf16 v[64:67], v[64:67], v[48:51], v[72:75]
	s_nop 2
	v_add_u32_e32 v72, v113, v108
	ds_read2_b64 v[72:75], v72 offset1:4
	s_waitcnt lgkmcnt(0)
; #define LAS __attribute__((address_space(3)))
; #define MFMA16(a, b, c) __builtin_amdgcn_mfma_f32_16x16x32_bf16((a), (b), (c), 0, 0, 0)
; __device__ __forceinline__ void xattn_pair(LAS unsigned char* lds, int bh, size_t row_base, bf16* QO, const bf16* Kx, const bf16* VTx, int tid, const WsRef& wsr) {
;     ...
;     for (int nh = 0; nh < 2; ++nh) {
;         f32x4 o0[8], o1[8];
; #pragma unroll
;         for (int n = 0; n < 8; ++n) { o0[n] = (f32x4){0.f, 0.f, 0.f, 0.f}; o1[n] = (f32x4){0.f, 0.f, 0.f, 0.f}; }
; #pragma unroll
;         for (int kk = 0; kk < 8; ++kk)
; #pragma unroll
;             for (int n = 0; n < 8; ++n) { const LAS bf16* vp = T + ((nh * 8 + n) * 16 + fr) * LDX + kk * 32 + 4 * fq;
;                 const u32x2 lo = *(const LAS u32x2*)vp, hi = *(const LAS u32x2*)(vp + 16); u32x4 w; w.x = lo.x; w.y = lo.y; w.z = hi.x; w.w = hi.y; const bf16x8 vf = __builtin_bit_cast(bf16x8, w);
;                 o0[n] = MFMA16(vf, pf0[kk], o0[n]); o1[n] = MFMA16(vf, pf1[kk], o1[n]); }
	v_mfma_f32_16x16x32_bf16 v[76:79], v[72:75], v[52:55], v[84:87]
	v_mfma_f32_16x16x32_bf16 v[72:75], v[72:75], v[48:51], v[80:83]
	s_nop 2
	v_add_u32_e32 v80, v113, v107
	ds_read2_b64 v[80:83], v80 offset1:4
	s_waitcnt lgkmcnt(0)
	v_mfma_f32_16x16x32_bf16 v[84:87], v[80:83], v[52:55], v[92:95]
	v_mfma_f32_16x16x32_bf16 v[80:83], v[80:83], v[48:51], v[88:91]
	s_nop 2
	v_add_u32_e32 v88, v113, v105
	ds_read2_b64 v[88:91], v88 offset1:4
	s_waitcnt lgkmcnt(0)
	v_mfma_f32_16x16x32_bf16 v[92:95], v[88:91], v[52:55], v[120:123]
	v_mfma_f32_16x16x32_bf16 v[88:91], v[88:91], v[48:51], v[116:119]
	s_nop 2
	ds_read2_b64 v[114:117], v99 offset1:4
	v_add_u32_e32 v99, v113, v101
	s_waitcnt lgkmcnt(0)
	v_mfma_f32_16x16x32_bf16 v[118:121], v[114:117], v[52:55], v[130:133]
	v_mfma_f32_16x16x32_bf16 v[114:117], v[114:117], v[48:51], v[124:127]
	s_nop 2
	ds_read2_b64 v[122:125], v99 offset1:4
	s_waitcnt lgkmcnt(0)
	v_mfma_f32_16x16x32_bf16 v[20:23], v[122:125], v[48:51], v[20:23]
	v_add_u32_e32 v48, v112, v97
	ds_read2_b64 v[48:51], v48 offset1:4
	v_add_u32_e32 v99, v112, v101
	s_waitcnt lgkmcnt(0)
	v_mfma_f32_16x16x32_bf16 v[32:35], v[48:51], v[60:63], v[32:35]
	v_mfma_f32_16x16x32_bf16 v[28:31], v[48:51], v[56:59], v[28:31]
	v_add_u32_e32 v48, v112, v103
	ds_read2_b64 v[48:51], v48 offset1:4
	s_waitcnt lgkmcnt(0)
	v_mfma_f32_16x16x32_bf16 v[44:47], v[48:51], v[60:63], v[44:47]
	v_mfma_f32_16x16x32_bf16 v[40:43], v[48:51], v[56:59], v[40:43]
	v_add_u32_e32 v48, v112, v106
	ds_read2_b64 v[48:51], v48 offset1:4
	v_mfma_f32_16x16x32_bf16 v[24:27], v[122:125], v[52:55], v[24:27]
	s_waitcnt lgkmcnt(0)
	v_mfma_f32_16x16x32_bf16 v[52:55], v[48:51], v[60:63], v[68:71]
	v_mfma_f32_16x16x32_bf16 v[48:51], v[48:51], v[56:59], v[64:67]
	s_nop 2
	v_add_u32_e32 v64, v112, v108
	ds_read2_b64 v[64:67], v64 offset1:4
	s_waitcnt lgkmcnt(0)
	v_mfma_f32_16x16x32_bf16 v[68:71], v[64:67], v[60:63], v[76:79]
	v_mfma_f32_16x16x32_bf16 v[64:67], v[64:67], v[56:59], v[72:75]
	s_nop 2
	v_add_u32_e32 v72, v112, v107
	ds_read2_b64 v[72:75], v72 offset1:4
	s_waitcnt lgkmcnt(0)
	v_mfma_f32_16x16x32_bf16 v[76:79], v[72:75], v[60:63], v[84:87]
	v_mfma_f32_16x16x32_bf16 v[72:75], v[72:75], v[56:59], v[80:83]
	s_nop 2
	v_add_u32_e32 v80, v112, v105
	ds_read2_b64 v[80:83], v80 offset1:4
	s_waitcnt lgkmcnt(0)
	v_mfma_f32_16x16x32_bf16 v[84:87], v[80:83], v[60:63], v[92:95]
	v_mfma_f32_16x16x32_bf16 v[80:83], v[80:83], v[56:59], v[88:91]
	s_nop 2
	v_add_u32_e32 v88, v112, v104
	ds_read2_b64 v[88:91], v88 offset1:4
	s_waitcnt lgkmcnt(0)
	v_mfma_f32_16x16x32_bf16 v[92:95], v[88:91], v[60:63], v[118:121]
	v_mfma_f32_16x16x32_bf16 v[88:91], v[88:91], v[56:59], v[114:117]
	s_nop 2
	ds_read2_b64 v[112:115], v99 offset1:4
	s_waitcnt lgkmcnt(0)
	v_mfma_f32_16x16x32_bf16 v[56:59], v[112:115], v[56:59], v[20:23]
	s_nop 2
	v_add_u32_e32 v20, v111, v97
	ds_read2_b64 v[20:23], v20 offset1:4
	v_add_u32_e32 v99, v110, v101
	v_mfma_f32_16x16x32_bf16 v[24:27], v[112:115], v[60:63], v[24:27]
	s_waitcnt lgkmcnt(0)
	v_mfma_f32_16x16x32_bf16 v[60:63], v[20:23], v[36:39], v[32:35]
	v_mfma_f32_16x16x32_bf16 v[112:115], v[20:23], v[16:19], v[28:31]
	v_add_u32_e32 v20, v111, v103
	ds_read2_b64 v[20:23], v20 offset1:4
	s_waitcnt lgkmcnt(0)
	v_mfma_f32_16x16x32_bf16 v[116:119], v[20:23], v[36:39], v[44:47]
	v_add_u32_e32 v28, v111, v105
	v_mfma_f32_16x16x32_bf16 v[120:123], v[20:23], v[16:19], v[40:43]
	v_add_u32_e32 v20, v111, v106
	ds_read2_b64 v[20:23], v20 offset1:4
	s_waitcnt lgkmcnt(0)
	v_mfma_f32_16x16x32_bf16 v[52:55], v[20:23], v[36:39], v[52:55]
	v_mfma_f32_16x16x32_bf16 v[48:51], v[20:23], v[16:19], v[48:51]
	v_add_u32_e32 v20, v111, v108
	ds_read2_b64 v[20:23], v20 offset1:4
	s_waitcnt lgkmcnt(0)
	v_mfma_f32_16x16x32_bf16 v[68:71], v[20:23], v[36:39], v[68:71]
	v_mfma_f32_16x16x32_bf16 v[64:67], v[20:23], v[16:19], v[64:67]
	v_add_u32_e32 v20, v111, v107
	ds_read2_b64 v[20:23], v20 offset1:4
	s_waitcnt lgkmcnt(0)
	v_mfma_f32_16x16x32_bf16 v[76:79], v[20:23], v[36:39], v[76:79]
	v_mfma_f32_16x16x32_bf16 v[44:47], v[20:23], v[16:19], v[72:75]
	ds_read2_b64 v[20:23], v28 offset1:4
	v_add_u32_e32 v28, v111, v104
	s_waitcnt lgkmcnt(0)
	v_mfma_f32_16x16x32_bf16 v[40:43], v[20:23], v[36:39], v[84:87]
	v_add_u32_e32 v72, v111, v101
	ds_read2_b64 v[72:75], v72 offset1:4
	s_nop 0
	v_add_u32_e32 v84, v110, v103
	v_mfma_f32_16x16x32_bf16 v[32:35], v[20:23], v[16:19], v[80:83]
	ds_read2_b64 v[20:23], v28 offset1:4
	ds_read2_b64 v[84:87], v84 offset1:4
	s_nop 0
	v_add_u32_e32 v80, v110, v97
	ds_read2_b64 v[80:83], v80 offset1:4
	v_add_u32_e32 v97, v109, v97
	ds_read2_b64 v[124:127], v97 offset1:4
	s_waitcnt lgkmcnt(3)
	v_mfma_f32_16x16x32_bf16 v[28:31], v[20:23], v[36:39], v[92:95]
	v_add_u32_e32 v97, v109, v103
	ds_read2_b64 v[130:133], v97 offset1:4
	v_add_u32_e32 v97, v109, v106
	v_mfma_f32_16x16x32_bf16 v[20:23], v[20:23], v[16:19], v[88:91]
	v_add_u32_e32 v92, v110, v104
	ds_read2_b64 v[92:95], v92 offset1:4
	s_nop 0
	v_add_u32_e32 v88, v110, v106
	v_mfma_f32_16x16x32_bf16 v[24:27], v[72:75], v[36:39], v[24:27]
	ds_read2_b64 v[36:39], v88 offset1:4
	v_add_u32_e32 v88, v110, v108
	ds_read2_b64 v[88:91], v88 offset1:4
	s_waitcnt lgkmcnt(5)
	v_mfma_f32_16x16x32_bf16 v[60:63], v[80:83], v[12:15], v[60:63]
	v_mfma_f32_16x16x32_bf16 v[80:83], v[80:83], v[4:7], v[112:115]
	s_waitcnt lgkmcnt(4)
; #define LAS __attribute__((address_space(3)))
; __device__ __forceinline__ unsigned pk2(float lo, float hi) { return pg8::cvt_pk_bf16(lo, hi); }
; __device__ __forceinline__ void wt_store8(const WsRef& w, const void* p, u32x2 v) { __builtin_amdgcn_raw_buffer_store_b64(v, w.r, (unsigned)((const unsigned char*)p - w.base), 0, 16); }
; #define MFMA16(a, b, c) __builtin_amdgcn_mfma_f32_16x16x32_bf16((a), (b), (c), 0, 0, 0)
; __device__ __forceinline__ void xattn_pair(LAS unsigned char* lds, int bh, size_t row_base, bf16* QO, const bf16* Kx, const bf16* VTx, int tid, const WsRef& wsr) {
;     ...
;     for (int nh = 0; nh < 2; ++nh) {
;         f32x4 o0[8], o1[8];
; #pragma unroll
;         for (int n = 0; n < 8; ++n) { o0[n] = (f32x4){0.f, 0.f, 0.f, 0.f}; o1[n] = (f32x4){0.f, 0.f, 0.f, 0.f}; }
; #pragma unroll
;         for (int kk = 0; kk < 8; ++kk)
; #pragma unroll
;             for (int n = 0; n < 8; ++n) { const LAS bf16* vp = T + ((nh * 8 + n) * 16 + fr) * LDX + kk * 32 + 4 * fq;
;                 const u32x2 lo = *(const LAS u32x2*)vp, hi = *(const LAS u32x2*)(vp + 16); u32x4 w; w.x = lo.x; w.y = lo.y; w.z = hi.x; w.w = hi.y; const bf16x8 vf = __builtin_bit_cast(bf16x8, w);
;                 o0[n] = MFMA16(vf, pf0[kk], o0[n]); o1[n] = MFMA16(vf, pf1[kk], o1[n]); }
; #pragma unroll
;         for (int n = 0; n < 8; ++n) { const f32x4 v0 = o0[n] * rinv0, v1 = o1[n] * rinv1; u32x2 w0, w1; w0.x = pk2(v0[0], v0[1]); w0.y = pk2(v0[2], v0[3]); w1.x = pk2(v1[0], v1[1]); w1.y = pk2(v1[2], v1[3]);
;             wt_store8(wsr, qp0 + (nh * 8 + n) * 16 + 4 * fq, w0); wt_store8(wsr, qp1 + (nh * 8 + n) * 16 + 4 * fq, w1); }
;         __builtin_amdgcn_sched_barrier(0);
;     }
	v_mfma_f32_16x16x32_bf16 v[60:63], v[124:127], v[8:11], v[60:63]
	v_mfma_f32_16x16x32_bf16 v[114:117], v[84:87], v[12:15], v[116:119]
	v_mfma_f32_16x16x32_bf16 v[84:87], v[84:87], v[4:7], v[120:123]
	s_nop 2
	ds_read2_b64 v[118:121], v97 offset1:4
	v_add_u32_e32 v97, v109, v108
	v_mfma_f32_16x16x32_bf16 v[80:83], v[124:127], v[0:3], v[80:83]
	ds_read2_b64 v[134:137], v97 offset1:4
	v_add_u32_e32 v97, v109, v107
	ds_read2_b64 v[138:141], v97 offset1:4
	v_add_u32_e32 v97, v109, v104
	v_mfma_f32_16x16x32_bf16 v[16:19], v[72:75], v[16:19], v[56:59]
	v_add_u32_e32 v72, v110, v105
	v_pk_mul_f32 v[122:123], v[102:103], v[60:61] op_sel_hi:[0,1]
	s_nop 0
	v_pk_mul_f32 v[82:83], v[100:101], v[82:83] op_sel_hi:[0,1]
	v_add_u32_e32 v56, v110, v107
	s_waitcnt lgkmcnt(4)
	v_mfma_f32_16x16x32_bf16 v[52:55], v[36:39], v[12:15], v[52:55]
	ds_read2_b64 v[56:59], v56 offset1:4
	ds_read2_b64 v[72:75], v72 offset1:4
	ds_read2_b64 v[110:113], v99 offset1:4
	v_mfma_f32_16x16x32_bf16 v[36:39], v[36:39], v[4:7], v[48:51]
	s_nop 2
	v_add_u32_e32 v48, v109, v105
	ds_read2_b64 v[104:107], v97 offset1:4
	v_add_u32_e32 v97, v109, v101
	v_pk_mul_f32 v[108:109], v[102:103], v[62:63] op_sel_hi:[0,1]
	s_waitcnt lgkmcnt(7)
	v_mfma_f32_16x16x32_bf16 v[60:63], v[88:91], v[12:15], v[68:71]
	ds_read2_b64 v[48:51], v48 offset1:4
	ds_read2_b64 v[142:145], v97 offset1:4
	s_nop 0
	v_pk_mul_f32 v[68:69], v[100:101], v[80:81] op_sel_hi:[0,1]
	v_cvt_pk_bf16_f32 v70, v122, v123
	v_cvt_pk_bf16_f32 v71, v108, v109
	v_cvt_pk_bf16_f32 v80, v68, v69
	buffer_store_dwordx2 v[70:71], v96, s[88:91], 0 offen offset:256 sc1
	v_mfma_f32_16x16x32_bf16 v[68:71], v[130:133], v[8:11], v[114:117]
	v_cvt_pk_bf16_f32 v81, v82, v83
	buffer_store_dwordx2 v[80:81], v98, s[88:91], 0 offen offset:256 sc1
	s_waitcnt lgkmcnt(8)
	v_mfma_f32_16x16x32_bf16 v[36:39], v[118:121], v[0:3], v[36:39]
	v_mfma_f32_16x16x32_bf16 v[52:55], v[118:121], v[8:11], v[52:55]
	s_nop 2
	v_mul_f32_e64 v80, v102, v70
	v_mul_f32_e64 v81, v102, v71
	v_pk_mul_f32 v[82:83], v[102:103], v[68:69] op_sel_hi:[0,1]
	v_cvt_pk_bf16_f32 v82, v82, v83
	v_mfma_f32_16x16x32_bf16 v[68:71], v[130:133], v[0:3], v[84:87]
	v_cvt_pk_bf16_f32 v83, v80, v81
	v_pk_mul_f32 v[54:55], v[102:103], v[54:55] op_sel_hi:[0,1]
	v_pk_mul_f32 v[52:53], v[102:103], v[52:53] op_sel_hi:[0,1]
	v_cvt_pk_bf16_f32 v52, v52, v53
	v_cvt_pk_bf16_f32 v53, v54, v55
	s_nop 2
	v_pk_mul_f32 v[84:85], v[100:101], v[70:71] op_sel_hi:[0,1]
	v_pk_mul_f32 v[86:87], v[100:101], v[68:69] op_sel_hi:[0,1]
	s_waitcnt lgkmcnt(5)
	v_mfma_f32_16x16x32_bf16 v[68:71], v[56:59], v[12:15], v[76:79]
	s_nop 2
	v_cvt_pk_bf16_f32 v76, v86, v87
	v_cvt_pk_bf16_f32 v77, v84, v85
	buffer_store_dwordx2 v[82:83], v96, s[88:91], 0 offen offset:288 sc1
	buffer_store_dwordx2 v[76:77], v98, s[88:91], 0 offen offset:288 sc1
	v_pk_mul_f32 v[76:77], v[100:101], v[38:39] op_sel_hi:[0,1]
	v_pk_mul_f32 v[78:79], v[100:101], v[36:37] op_sel_hi:[0,1]
	v_mfma_f32_16x16x32_bf16 v[36:39], v[56:59], v[4:7], v[44:47]
	v_cvt_pk_bf16_f32 v54, v78, v79
	v_cvt_pk_bf16_f32 v55, v76, v77
	buffer_store_dwordx2 v[52:53], v96, s[88:91], 0 offen offset:320 sc1
	buffer_store_dwordx2 v[54:55], v98, s[88:91], 0 offen offset:320 sc1
	v_mfma_f32_16x16x32_bf16 v[44:47], v[134:137], v[8:11], v[60:63]
	v_mfma_f32_16x16x32_bf16 v[36:39], v[138:141], v[0:3], v[36:39]
	v_mfma_f32_16x16x32_bf16 v[64:67], v[88:91], v[4:7], v[64:67]
	s_nop 5
	v_mul_f32_e64 v46, v102, v46
	v_mul_f32_e64 v47, v102, v47
	v_pk_mul_f32 v[44:45], v[102:103], v[44:45] op_sel_hi:[0,1]
	v_cvt_pk_bf16_f32 v44, v44, v45
	v_cvt_pk_bf16_f32 v45, v46, v47
	buffer_store_dwordx2 v[44:45], v96, s[88:91], 0 offen offset:352 sc1
	v_mfma_f32_16x16x32_bf16 v[44:47], v[138:141], v[8:11], v[68:71]
	v_mul_f32_e64 v38, v100, v38
	v_mul_f32_e64 v39, v100, v39
	v_pk_mul_f32 v[36:37], v[100:101], v[36:37] op_sel_hi:[0,1]
	s_waitcnt lgkmcnt(4)
	v_mfma_f32_16x16x32_bf16 v[40:43], v[72:75], v[12:15], v[40:43]
	v_mfma_f32_16x16x32_bf16 v[28:31], v[92:95], v[12:15], v[28:31]
	s_nop 1
	v_mul_f32_e64 v46, v102, v46
	v_mul_f32_e64 v47, v102, v47
	v_pk_mul_f32 v[44:45], v[102:103], v[44:45] op_sel_hi:[0,1]
	v_cvt_pk_bf16_f32 v44, v44, v45
	v_mfma_f32_16x16x32_bf16 v[20:23], v[92:95], v[4:7], v[20:23]
	v_cvt_pk_bf16_f32 v45, v46, v47
	v_cvt_pk_bf16_f32 v46, v36, v37
	v_cvt_pk_bf16_f32 v47, v38, v39
	s_waitcnt lgkmcnt(3)
	v_mfma_f32_16x16x32_bf16 v[12:15], v[110:113], v[12:15], v[24:27]
	v_mfma_f32_16x16x32_bf16 v[32:35], v[72:75], v[4:7], v[32:35]
	v_mfma_f32_16x16x32_bf16 v[4:7], v[110:113], v[4:7], v[16:19]
	v_mfma_f32_16x16x32_bf16 v[52:55], v[134:137], v[0:3], v[64:67]
	s_waitcnt lgkmcnt(1)
	v_mfma_f32_16x16x32_bf16 v[36:39], v[48:51], v[8:11], v[40:43]
	v_mfma_f32_16x16x32_bf16 v[28:31], v[104:107], v[8:11], v[28:31]
	s_nop 4
	v_mul_f32_e64 v54, v100, v54
	v_mul_f32_e64 v55, v100, v55
	v_pk_mul_f32 v[52:53], v[100:101], v[52:53] op_sel_hi:[0,1]
	v_pk_mul_f32 v[38:39], v[102:103], v[38:39] op_sel_hi:[0,1]
	v_mfma_f32_16x16x32_bf16 v[20:23], v[104:107], v[0:3], v[20:23]
	v_mul_f32_e64 v36, v102, v36
	v_mul_f32_e64 v37, v102, v37
	v_pk_mul_f32 v[30:31], v[102:103], v[30:31] op_sel_hi:[0,1]
	v_pk_mul_f32 v[28:29], v[102:103], v[28:29] op_sel_hi:[0,1]
	s_waitcnt lgkmcnt(0)
	v_mfma_f32_16x16x32_bf16 v[8:11], v[142:145], v[8:11], v[12:15]
	v_cvt_pk_bf16_f32 v52, v52, v53
	s_nop 0
	v_pk_mul_f32 v[22:23], v[100:101], v[22:23] op_sel_hi:[0,1]
	v_pk_mul_f32 v[20:21], v[100:101], v[20:21] op_sel_hi:[0,1]
	v_mfma_f32_16x16x32_bf16 v[32:35], v[48:51], v[0:3], v[32:35]
	v_cvt_pk_bf16_f32 v53, v54, v55
	s_nop 1
	v_pk_mul_f32 v[10:11], v[102:103], v[10:11] op_sel_hi:[0,1]
	v_pk_mul_f32 v[8:9], v[102:103], v[8:9] op_sel_hi:[0,1]
	v_mfma_f32_16x16x32_bf16 v[0:3], v[142:145], v[0:3], v[4:7]
	v_cvt_pk_bf16_f32 v36, v36, v37
	s_nop 0
	v_pk_mul_f32 v[34:35], v[100:101], v[34:35] op_sel_hi:[0,1]
	v_pk_mul_f32 v[32:33], v[100:101], v[32:33] op_sel_hi:[0,1]
	v_cvt_pk_bf16_f32 v37, v38, v39
	v_cvt_pk_bf16_f32 v24, v28, v29
	v_cvt_pk_bf16_f32 v25, v30, v31
	v_cvt_pk_bf16_f32 v16, v20, v21
	v_cvt_pk_bf16_f32 v17, v22, v23
	v_pk_mul_f32 v[2:3], v[100:101], v[2:3] op_sel_hi:[0,1]
	v_pk_mul_f32 v[0:1], v[100:101], v[0:1] op_sel_hi:[0,1]
	v_cvt_pk_bf16_f32 v4, v8, v9
	v_cvt_pk_bf16_f32 v5, v10, v11
	buffer_store_dwordx2 v[52:53], v98, s[88:91], 0 offen offset:352 sc1
	buffer_store_dwordx2 v[44:45], v96, s[88:91], 0 offen offset:384 sc1
	buffer_store_dwordx2 v[46:47], v98, s[88:91], 0 offen offset:384 sc1
	v_cvt_pk_bf16_f32 v32, v32, v33
	v_cvt_pk_bf16_f32 v33, v34, v35
	buffer_store_dwordx2 v[36:37], v96, s[88:91], 0 offen offset:416 sc1
	buffer_store_dwordx2 v[32:33], v98, s[88:91], 0 offen offset:416 sc1
	buffer_store_dwordx2 v[24:25], v96, s[88:91], 0 offen offset:448 sc1
	buffer_store_dwordx2 v[16:17], v98, s[88:91], 0 offen offset:448 sc1
	v_cvt_pk_bf16_f32 v0, v0, v1
	v_cvt_pk_bf16_f32 v1, v2, v3
	buffer_store_dwordx2 v[4:5], v96, s[88:91], 0 offen offset:480 sc1
	buffer_store_dwordx2 v[0:1], v98, s[88:91], 0 offen offset:480 sc1
	s_branch .Lpp8_done
